# mod item silu(c) staging: 16 loads in flight with counted waits (on top of peel/noinv)
# baseline (speedup 1.0000x reference)
; #define LAS __attribute__((address_space(3)))
; __device__ __forceinline__ void p0_mod_item(const Params& p, LAS unsigned char* lds, int item) {
;     LAS float* cs = (LAS float*)lds;
;     LAS float* red = (LAS float*)(lds + 32768);
;     const int tid = threadIdx.x;
;     for (int u = tid; u < NBATCH * DM; u += NTHREADS) { const float v = p.c[u]; cs[u] = v / (1.0f + __expf(-v)); }
.LBB0_28:
	global_load_dword v208, v[0:1], off
	v_lshl_add_u64 v[0:1], v[0:1], 0, s[4:5]
	global_load_dword v209, v[0:1], off
	v_lshl_add_u64 v[0:1], v[0:1], 0, s[4:5]
	global_load_dword v210, v[0:1], off
	v_lshl_add_u64 v[0:1], v[0:1], 0, s[4:5]
	global_load_dword v211, v[0:1], off
	v_lshl_add_u64 v[0:1], v[0:1], 0, s[4:5]
	global_load_dword v212, v[0:1], off
	v_lshl_add_u64 v[0:1], v[0:1], 0, s[4:5]
	global_load_dword v213, v[0:1], off
	v_lshl_add_u64 v[0:1], v[0:1], 0, s[4:5]
	global_load_dword v214, v[0:1], off
	v_lshl_add_u64 v[0:1], v[0:1], 0, s[4:5]
	global_load_dword v215, v[0:1], off
	v_lshl_add_u64 v[0:1], v[0:1], 0, s[4:5]
	global_load_dword v216, v[0:1], off
	v_lshl_add_u64 v[0:1], v[0:1], 0, s[4:5]
	global_load_dword v217, v[0:1], off
	v_lshl_add_u64 v[0:1], v[0:1], 0, s[4:5]
	global_load_dword v218, v[0:1], off
	v_lshl_add_u64 v[0:1], v[0:1], 0, s[4:5]
	global_load_dword v219, v[0:1], off
	v_lshl_add_u64 v[0:1], v[0:1], 0, s[4:5]
	global_load_dword v220, v[0:1], off
	v_lshl_add_u64 v[0:1], v[0:1], 0, s[4:5]
	global_load_dword v221, v[0:1], off
	v_lshl_add_u64 v[0:1], v[0:1], 0, s[4:5]
	global_load_dword v222, v[0:1], off
	v_lshl_add_u64 v[0:1], v[0:1], 0, s[4:5]
	global_load_dword v223, v[0:1], off
	s_waitcnt vmcnt(15)
	v_mul_f32_e32 v5, 0xbfb8aa3b, v208
	v_exp_f32_e32 v5, v5
	s_nop 0
	v_add_f32_e32 v5, 1.0, v5
	v_div_scale_f32 v6, s[10:11], v5, v5, v208
	v_rcp_f32_e32 v7, v6
	v_div_scale_f32 v8, vcc, v208, v5, v208
	v_fma_f32 v9, -v6, v7, 1.0
	v_fmac_f32_e32 v7, v9, v7
	v_mul_f32_e32 v9, v8, v7
	v_fma_f32 v10, -v6, v9, v8
	v_fmac_f32_e32 v9, v10, v7
	v_fma_f32 v6, -v6, v9, v8
	v_div_fmas_f32 v6, v6, v7, v9
	v_div_fixup_f32 v4, v6, v5, v208
	ds_write_b32 v2, v4
	s_waitcnt vmcnt(14)
	v_mul_f32_e32 v5, 0xbfb8aa3b, v209
	v_exp_f32_e32 v5, v5
	s_nop 0
	v_add_f32_e32 v5, 1.0, v5
	v_div_scale_f32 v6, s[10:11], v5, v5, v209
	v_rcp_f32_e32 v7, v6
	v_div_scale_f32 v8, vcc, v209, v5, v209
	v_fma_f32 v9, -v6, v7, 1.0
	v_fmac_f32_e32 v7, v9, v7
	v_mul_f32_e32 v9, v8, v7
	v_fma_f32 v10, -v6, v9, v8
	v_fmac_f32_e32 v9, v10, v7
	v_fma_f32 v6, -v6, v9, v8
	v_div_fmas_f32 v6, v6, v7, v9
	v_div_fixup_f32 v4, v6, v5, v209
	ds_write_b32 v2, v4 offset:2048
	s_waitcnt vmcnt(13)
	v_mul_f32_e32 v5, 0xbfb8aa3b, v210
	v_exp_f32_e32 v5, v5
	s_nop 0
	v_add_f32_e32 v5, 1.0, v5
	v_div_scale_f32 v6, s[10:11], v5, v5, v210
	v_rcp_f32_e32 v7, v6
	v_div_scale_f32 v8, vcc, v210, v5, v210
	v_fma_f32 v9, -v6, v7, 1.0
	v_fmac_f32_e32 v7, v9, v7
	v_mul_f32_e32 v9, v8, v7
	v_fma_f32 v10, -v6, v9, v8
	v_fmac_f32_e32 v9, v10, v7
	v_fma_f32 v6, -v6, v9, v8
	v_div_fmas_f32 v6, v6, v7, v9
	v_div_fixup_f32 v4, v6, v5, v210
	ds_write_b32 v2, v4 offset:4096
	s_waitcnt vmcnt(12)
	v_mul_f32_e32 v5, 0xbfb8aa3b, v211
	v_exp_f32_e32 v5, v5
	s_nop 0
	v_add_f32_e32 v5, 1.0, v5
	v_div_scale_f32 v6, s[10:11], v5, v5, v211
	v_rcp_f32_e32 v7, v6
	v_div_scale_f32 v8, vcc, v211, v5, v211
	v_fma_f32 v9, -v6, v7, 1.0
	v_fmac_f32_e32 v7, v9, v7
	v_mul_f32_e32 v9, v8, v7
	v_fma_f32 v10, -v6, v9, v8
	v_fmac_f32_e32 v9, v10, v7
	v_fma_f32 v6, -v6, v9, v8
	v_div_fmas_f32 v6, v6, v7, v9
	v_div_fixup_f32 v4, v6, v5, v211
	ds_write_b32 v2, v4 offset:6144
	s_waitcnt vmcnt(11)
	v_mul_f32_e32 v5, 0xbfb8aa3b, v212
	v_exp_f32_e32 v5, v5
	s_nop 0
	v_add_f32_e32 v5, 1.0, v5
	v_div_scale_f32 v6, s[10:11], v5, v5, v212
	v_rcp_f32_e32 v7, v6
	v_div_scale_f32 v8, vcc, v212, v5, v212
	v_fma_f32 v9, -v6, v7, 1.0
	v_fmac_f32_e32 v7, v9, v7
	v_mul_f32_e32 v9, v8, v7
	v_fma_f32 v10, -v6, v9, v8
	v_fmac_f32_e32 v9, v10, v7
	v_fma_f32 v6, -v6, v9, v8
	v_div_fmas_f32 v6, v6, v7, v9
	v_div_fixup_f32 v4, v6, v5, v212
	ds_write_b32 v2, v4 offset:8192
	s_waitcnt vmcnt(10)
	v_mul_f32_e32 v5, 0xbfb8aa3b, v213
	v_exp_f32_e32 v5, v5
	s_nop 0
	v_add_f32_e32 v5, 1.0, v5
	v_div_scale_f32 v6, s[10:11], v5, v5, v213
	v_rcp_f32_e32 v7, v6
	v_div_scale_f32 v8, vcc, v213, v5, v213
	v_fma_f32 v9, -v6, v7, 1.0
	v_fmac_f32_e32 v7, v9, v7
	v_mul_f32_e32 v9, v8, v7
	v_fma_f32 v10, -v6, v9, v8
	v_fmac_f32_e32 v9, v10, v7
	v_fma_f32 v6, -v6, v9, v8
	v_div_fmas_f32 v6, v6, v7, v9
	v_div_fixup_f32 v4, v6, v5, v213
	ds_write_b32 v2, v4 offset:10240
	s_waitcnt vmcnt(9)
	v_mul_f32_e32 v5, 0xbfb8aa3b, v214
	v_exp_f32_e32 v5, v5
	s_nop 0
	v_add_f32_e32 v5, 1.0, v5
	v_div_scale_f32 v6, s[10:11], v5, v5, v214
	v_rcp_f32_e32 v7, v6
	v_div_scale_f32 v8, vcc, v214, v5, v214
	v_fma_f32 v9, -v6, v7, 1.0
	v_fmac_f32_e32 v7, v9, v7
	v_mul_f32_e32 v9, v8, v7
	v_fma_f32 v10, -v6, v9, v8
	v_fmac_f32_e32 v9, v10, v7
	v_fma_f32 v6, -v6, v9, v8
	v_div_fmas_f32 v6, v6, v7, v9
	v_div_fixup_f32 v4, v6, v5, v214
	ds_write_b32 v2, v4 offset:12288
	s_waitcnt vmcnt(8)
	v_mul_f32_e32 v5, 0xbfb8aa3b, v215
	v_exp_f32_e32 v5, v5
	s_nop 0
	v_add_f32_e32 v5, 1.0, v5
	v_div_scale_f32 v6, s[10:11], v5, v5, v215
	v_rcp_f32_e32 v7, v6
	v_div_scale_f32 v8, vcc, v215, v5, v215
	v_fma_f32 v9, -v6, v7, 1.0
	v_fmac_f32_e32 v7, v9, v7
	v_mul_f32_e32 v9, v8, v7
	v_fma_f32 v10, -v6, v9, v8
	v_fmac_f32_e32 v9, v10, v7
	v_fma_f32 v6, -v6, v9, v8
	v_div_fmas_f32 v6, v6, v7, v9
	v_div_fixup_f32 v4, v6, v5, v215
	ds_write_b32 v2, v4 offset:14336
	s_waitcnt vmcnt(7)
	v_mul_f32_e32 v5, 0xbfb8aa3b, v216
	v_exp_f32_e32 v5, v5
	s_nop 0
	v_add_f32_e32 v5, 1.0, v5
	v_div_scale_f32 v6, s[10:11], v5, v5, v216
	v_rcp_f32_e32 v7, v6
	v_div_scale_f32 v8, vcc, v216, v5, v216
	v_fma_f32 v9, -v6, v7, 1.0
	v_fmac_f32_e32 v7, v9, v7
	v_mul_f32_e32 v9, v8, v7
	v_fma_f32 v10, -v6, v9, v8
	v_fmac_f32_e32 v9, v10, v7
	v_fma_f32 v6, -v6, v9, v8
	v_div_fmas_f32 v6, v6, v7, v9
	v_div_fixup_f32 v4, v6, v5, v216
	ds_write_b32 v2, v4 offset:16384
	s_waitcnt vmcnt(6)
; __device__ __forceinline__ void p0_mod_item(const Params& p, LAS unsigned char* lds, int item) {
;     ...
;     for (int u = tid; u < NBATCH * DM; u += NTHREADS) { const float v = p.c[u]; cs[u] = v / (1.0f + __expf(-v)); }
;     __syncthreads();
;     const int j0 = item * 64, l16 = tid & 15, rs = tid >> 4;
;     f32x4 acc[8];
; #pragma unroll
;     for (int b = 0; b < 8; ++b) acc[b] = (f32x4){0.f, 0.f, 0.f, 0.f};
; #pragma unroll 32
;     for (int pass = 0; pass < 32; ++pass) { const int i = pass * 32 + rs; const f32x4 w = *(const f32x4*)(p.w_ada + (size_t)i * NMOD + j0 + 4 * l16);
; #pragma unroll
;         for (int b = 0; b < 8; ++b) acc[b] += cs[b * DM + i] * w; }
	v_mul_f32_e32 v5, 0xbfb8aa3b, v217
	v_exp_f32_e32 v5, v5
	s_nop 0
	v_add_f32_e32 v5, 1.0, v5
	v_div_scale_f32 v6, s[10:11], v5, v5, v217
	v_rcp_f32_e32 v7, v6
	v_div_scale_f32 v8, vcc, v217, v5, v217
	v_fma_f32 v9, -v6, v7, 1.0
	v_fmac_f32_e32 v7, v9, v7
	v_mul_f32_e32 v9, v8, v7
	v_fma_f32 v10, -v6, v9, v8
	v_fmac_f32_e32 v9, v10, v7
	v_fma_f32 v6, -v6, v9, v8
	v_div_fmas_f32 v6, v6, v7, v9
	v_div_fixup_f32 v4, v6, v5, v217
	ds_write_b32 v2, v4 offset:18432
	s_waitcnt vmcnt(5)
	v_mul_f32_e32 v5, 0xbfb8aa3b, v218
	v_exp_f32_e32 v5, v5
	s_nop 0
	v_add_f32_e32 v5, 1.0, v5
	v_div_scale_f32 v6, s[10:11], v5, v5, v218
	v_rcp_f32_e32 v7, v6
	v_div_scale_f32 v8, vcc, v218, v5, v218
	v_fma_f32 v9, -v6, v7, 1.0
	v_fmac_f32_e32 v7, v9, v7
	v_mul_f32_e32 v9, v8, v7
	v_fma_f32 v10, -v6, v9, v8
	v_fmac_f32_e32 v9, v10, v7
	v_fma_f32 v6, -v6, v9, v8
	v_div_fmas_f32 v6, v6, v7, v9
	v_div_fixup_f32 v4, v6, v5, v218
	ds_write_b32 v2, v4 offset:20480
	s_waitcnt vmcnt(4)
	v_mul_f32_e32 v5, 0xbfb8aa3b, v219
	v_exp_f32_e32 v5, v5
	s_nop 0
	v_add_f32_e32 v5, 1.0, v5
	v_div_scale_f32 v6, s[10:11], v5, v5, v219
	v_rcp_f32_e32 v7, v6
	v_div_scale_f32 v8, vcc, v219, v5, v219
	v_fma_f32 v9, -v6, v7, 1.0
	v_fmac_f32_e32 v7, v9, v7
	v_mul_f32_e32 v9, v8, v7
	v_fma_f32 v10, -v6, v9, v8
	v_fmac_f32_e32 v9, v10, v7
	v_fma_f32 v6, -v6, v9, v8
	v_div_fmas_f32 v6, v6, v7, v9
	v_div_fixup_f32 v4, v6, v5, v219
	ds_write_b32 v2, v4 offset:22528
	s_waitcnt vmcnt(3)
	v_mul_f32_e32 v5, 0xbfb8aa3b, v220
	v_exp_f32_e32 v5, v5
	s_nop 0
	v_add_f32_e32 v5, 1.0, v5
	v_div_scale_f32 v6, s[10:11], v5, v5, v220
	v_rcp_f32_e32 v7, v6
	v_div_scale_f32 v8, vcc, v220, v5, v220
	v_fma_f32 v9, -v6, v7, 1.0
	v_fmac_f32_e32 v7, v9, v7
	v_mul_f32_e32 v9, v8, v7
	v_fma_f32 v10, -v6, v9, v8
	v_fmac_f32_e32 v9, v10, v7
	v_fma_f32 v6, -v6, v9, v8
	v_div_fmas_f32 v6, v6, v7, v9
	v_div_fixup_f32 v4, v6, v5, v220
	ds_write_b32 v2, v4 offset:24576
	s_waitcnt vmcnt(2)
	v_mul_f32_e32 v5, 0xbfb8aa3b, v221
	v_exp_f32_e32 v5, v5
	s_nop 0
	v_add_f32_e32 v5, 1.0, v5
	v_div_scale_f32 v6, s[10:11], v5, v5, v221
	v_rcp_f32_e32 v7, v6
	v_div_scale_f32 v8, vcc, v221, v5, v221
	v_fma_f32 v9, -v6, v7, 1.0
	v_fmac_f32_e32 v7, v9, v7
	v_mul_f32_e32 v9, v8, v7
	v_fma_f32 v10, -v6, v9, v8
	v_fmac_f32_e32 v9, v10, v7
	v_fma_f32 v6, -v6, v9, v8
	v_div_fmas_f32 v6, v6, v7, v9
	v_div_fixup_f32 v4, v6, v5, v221
	ds_write_b32 v2, v4 offset:26624
	s_waitcnt vmcnt(1)
	v_mul_f32_e32 v5, 0xbfb8aa3b, v222
	v_exp_f32_e32 v5, v5
	s_nop 0
	v_add_f32_e32 v5, 1.0, v5
	v_div_scale_f32 v6, s[10:11], v5, v5, v222
	v_rcp_f32_e32 v7, v6
	v_div_scale_f32 v8, vcc, v222, v5, v222
	v_fma_f32 v9, -v6, v7, 1.0
	v_fmac_f32_e32 v7, v9, v7
	v_mul_f32_e32 v9, v8, v7
	v_fma_f32 v10, -v6, v9, v8
	v_fmac_f32_e32 v9, v10, v7
	v_fma_f32 v6, -v6, v9, v8
	v_div_fmas_f32 v6, v6, v7, v9
	v_div_fixup_f32 v4, v6, v5, v222
	ds_write_b32 v2, v4 offset:28672
	s_waitcnt vmcnt(0)
	v_mul_f32_e32 v5, 0xbfb8aa3b, v223
	v_exp_f32_e32 v5, v5
	s_nop 0
	v_add_f32_e32 v5, 1.0, v5
	v_div_scale_f32 v6, s[10:11], v5, v5, v223
	v_rcp_f32_e32 v7, v6
	v_div_scale_f32 v8, vcc, v223, v5, v223
	v_fma_f32 v9, -v6, v7, 1.0
	v_fmac_f32_e32 v7, v9, v7
	v_mul_f32_e32 v9, v8, v7
	v_fma_f32 v10, -v6, v9, v8
	v_fmac_f32_e32 v9, v10, v7
	v_fma_f32 v6, -v6, v9, v8
	v_div_fmas_f32 v6, v6, v7, v9
	v_div_fixup_f32 v4, v6, v5, v223
	ds_write_b32 v2, v4 offset:30720
	s_or_b64 exec, exec, s[14:15]
	s_lshl_b32 s14, s23, 6
	s_ashr_i32 s15, s14, 31
	v_lshl_add_u64 v[100:101], s[14:15], 2, v[30:31]
	v_lshl_add_u64 v[8:9], v[100:101], 0, v[44:45]
	v_add_co_u32_e32 v4, vcc, s20, v8
	s_waitcnt lgkmcnt(0)
	s_barrier
	global_load_dwordx4 v[0:3], v[8:9], off
	v_addc_co_u32_e32 v5, vcc, 0, v9, vcc
	global_load_dwordx4 v[12:15], v[4:5], off
	v_add_co_u32_e32 v4, vcc, s21, v8
	v_lshl_add_u64 v[16:17], v[100:101], 0, v[46:47]
	s_nop 0
	v_addc_co_u32_e32 v5, vcc, 0, v9, vcc
	v_add_co_u32_e32 v8, vcc, s22, v8
	global_load_dwordx4 v[4:7], v[4:5], off
	s_nop 0
	v_addc_co_u32_e32 v9, vcc, 0, v9, vcc
	global_load_dwordx4 v[8:11], v[8:9], off
	v_lshl_add_u64 v[18:19], v[100:101], 0, v[48:49]
	ds_read2_b32 v[104:105], v126 offset1:32
	v_add_u32_e32 v79, 0x1000, v126
	v_add_u32_e32 v77, 0x2000, v126
	v_add_u32_e32 v75, 0x3000, v126
	v_add_u32_e32 v73, 0x4000, v126
	v_add_u32_e32 v71, 0x5000, v126
	v_add_u32_e32 v69, 0x6000, v126
	v_add_u32_e32 v81, 0x7000, v126
	ds_read2_b32 v[24:25], v126 offset0:64 offset1:96
	ds_read2_b32 v[156:157], v79 offset1:32
	ds_read2_b32 v[158:159], v77 offset1:32
	ds_read2_b32 v[160:161], v75 offset1:32
	ds_read2_b32 v[162:163], v73 offset1:32
	ds_read2_b32 v[164:165], v71 offset1:32
	ds_read2_b32 v[166:167], v69 offset1:32
	ds_read2_b32 v[168:169], v81 offset1:32
	ds_read2_b32 v[102:103], v79 offset0:64 offset1:96
	ds_read2_b32 v[26:27], v77 offset0:64 offset1:96
	global_load_dwordx4 v[20:23], v[16:17], off
	s_nop 0
	global_load_dwordx4 v[16:19], v[18:19], off
	s_waitcnt lgkmcnt(10)
	v_mov_b32_e32 v174, v105
	s_waitcnt lgkmcnt(8)
	v_mov_b32_e32 v176, v157
	s_waitcnt lgkmcnt(7)
	v_mov_b32_e32 v178, v159
	s_waitcnt lgkmcnt(6)
	v_mov_b32_e32 v180, v161
	s_waitcnt lgkmcnt(5)
	v_mov_b32_e32 v182, v163
	s_waitcnt lgkmcnt(4)
	v_mov_b32_e32 v184, v165
	s_waitcnt lgkmcnt(3)
	v_mov_b32_e32 v186, v167
	s_waitcnt lgkmcnt(2)
	v_mov_b32_e32 v188, v169
	v_add_u32_e32 v87, 0x800, v126
	v_add_u32_e32 v89, 0x1800, v126
	v_add_u32_e32 v91, 0x2800, v126
	v_add_u32_e32 v93, 0x3800, v126
	v_mov_b32_e32 v83, v29
	v_mov_b32_e32 v85, v29
	v_mov_b32_e32 v95, v29
	v_mov_b32_e32 v97, v29
	v_mov_b32_e32 v99, v29
	s_mov_b32 s10, 0
	s_waitcnt vmcnt(5)
; __device__ __forceinline__ void p0_mod_item(const Params& p, LAS unsigned char* lds, int item) {
;     ...
; #pragma unroll 32
;     for (int pass = 0; pass < 32; ++pass) { const int i = pass * 32 + rs; const f32x4 w = *(const f32x4*)(p.w_ada + (size_t)i * NMOD + j0 + 4 * l16);
; #pragma unroll
;         for (int b = 0; b < 8; ++b) acc[b] += cs[b * DM + i] * w; }
	v_pk_fma_f32 v[190:191], v[2:3], v[104:105], 0 op_sel_hi:[1,0,0]
	v_pk_fma_f32 v[104:105], v[0:1], v[104:105], 0 op_sel_hi:[1,0,0]
	v_pk_fma_f32 v[192:193], v[2:3], v[156:157], 0 op_sel_hi:[1,0,0]
	v_pk_fma_f32 v[156:157], v[0:1], v[156:157], 0 op_sel_hi:[1,0,0]
	v_pk_fma_f32 v[194:195], v[2:3], v[158:159], 0 op_sel_hi:[1,0,0]
	v_pk_fma_f32 v[158:159], v[0:1], v[158:159], 0 op_sel_hi:[1,0,0]
	v_pk_fma_f32 v[196:197], v[2:3], v[160:161], 0 op_sel_hi:[1,0,0]
	v_pk_fma_f32 v[160:161], v[0:1], v[160:161], 0 op_sel_hi:[1,0,0]
	v_pk_fma_f32 v[198:199], v[2:3], v[162:163], 0 op_sel_hi:[1,0,0]
	v_pk_fma_f32 v[162:163], v[0:1], v[162:163], 0 op_sel_hi:[1,0,0]
	v_pk_fma_f32 v[200:201], v[2:3], v[164:165], 0 op_sel_hi:[1,0,0]
	v_pk_fma_f32 v[164:165], v[0:1], v[164:165], 0 op_sel_hi:[1,0,0]
	v_pk_fma_f32 v[202:203], v[2:3], v[166:167], 0 op_sel_hi:[1,0,0]
	v_pk_fma_f32 v[166:167], v[0:1], v[166:167], 0 op_sel_hi:[1,0,0]
	v_pk_fma_f32 v[2:3], v[2:3], v[168:169], 0 op_sel_hi:[1,0,0]
	v_pk_fma_f32 v[0:1], v[0:1], v[168:169], 0 op_sel_hi:[1,0,0]
	s_waitcnt vmcnt(4)
	v_pk_fma_f32 v[168:169], v[14:15], v[174:175], v[190:191] op_sel_hi:[1,0,1]
	v_pk_fma_f32 v[104:105], v[12:13], v[174:175], v[104:105] op_sel_hi:[1,0,1]
	v_pk_fma_f32 v[174:175], v[14:15], v[176:177], v[192:193] op_sel_hi:[1,0,1]
	v_pk_fma_f32 v[156:157], v[12:13], v[176:177], v[156:157] op_sel_hi:[1,0,1]
	v_pk_fma_f32 v[176:177], v[14:15], v[178:179], v[194:195] op_sel_hi:[1,0,1]
	v_pk_fma_f32 v[158:159], v[12:13], v[178:179], v[158:159] op_sel_hi:[1,0,1]
	v_pk_fma_f32 v[178:179], v[14:15], v[180:181], v[196:197] op_sel_hi:[1,0,1]
	v_pk_fma_f32 v[160:161], v[12:13], v[180:181], v[160:161] op_sel_hi:[1,0,1]
	v_pk_fma_f32 v[180:181], v[14:15], v[182:183], v[198:199] op_sel_hi:[1,0,1]
	v_pk_fma_f32 v[162:163], v[12:13], v[182:183], v[162:163] op_sel_hi:[1,0,1]
	v_pk_fma_f32 v[182:183], v[14:15], v[184:185], v[200:201] op_sel_hi:[1,0,1]
	v_pk_fma_f32 v[164:165], v[12:13], v[184:185], v[164:165] op_sel_hi:[1,0,1]
	v_pk_fma_f32 v[184:185], v[14:15], v[186:187], v[202:203] op_sel_hi:[1,0,1]
	v_pk_fma_f32 v[166:167], v[12:13], v[186:187], v[166:167] op_sel_hi:[1,0,1]
	v_pk_fma_f32 v[2:3], v[14:15], v[188:189], v[2:3] op_sel_hi:[1,0,1]
	v_pk_fma_f32 v[0:1], v[12:13], v[188:189], v[0:1] op_sel_hi:[1,0,1]
	ds_read2_b32 v[186:187], v75 offset0:64 offset1:96
	ds_read2_b32 v[188:189], v73 offset0:64 offset1:96
	ds_read2_b32 v[190:191], v71 offset0:64 offset1:96
	ds_read2_b32 v[192:193], v69 offset0:64 offset1:96
	ds_read2_b32 v[194:195], v81 offset0:64 offset1:96
	s_waitcnt vmcnt(3)
	v_pk_fma_f32 v[168:169], v[6:7], v[24:25], v[168:169] op_sel_hi:[1,0,1]
	v_pk_fma_f32 v[104:105], v[4:5], v[24:25], v[104:105] op_sel_hi:[1,0,1]
	s_waitcnt lgkmcnt(6)
	v_pk_fma_f32 v[156:157], v[4:5], v[102:103], v[156:157] op_sel_hi:[1,0,1]
	s_waitcnt lgkmcnt(5)
	v_pk_fma_f32 v[158:159], v[4:5], v[26:27], v[158:159] op_sel_hi:[1,0,1]
	s_waitcnt lgkmcnt(4)
	v_pk_fma_f32 v[160:161], v[4:5], v[186:187], v[160:161] op_sel_hi:[1,0,1]
	s_waitcnt lgkmcnt(3)
	v_pk_fma_f32 v[162:163], v[4:5], v[188:189], v[162:163] op_sel_hi:[1,0,1]
	s_waitcnt lgkmcnt(2)
	v_pk_fma_f32 v[164:165], v[4:5], v[190:191], v[164:165] op_sel_hi:[1,0,1]
	s_waitcnt lgkmcnt(1)
	v_pk_fma_f32 v[166:167], v[4:5], v[192:193], v[166:167] op_sel_hi:[1,0,1]
	s_waitcnt lgkmcnt(0)
	v_pk_fma_f32 v[0:1], v[4:5], v[194:195], v[0:1] op_sel_hi:[1,0,1]
	v_mov_b32_e32 v4, v25
	v_pk_fma_f32 v[174:175], v[6:7], v[102:103], v[174:175] op_sel_hi:[1,0,1]
	s_waitcnt vmcnt(2)
	v_pk_fma_f32 v[24:25], v[10:11], v[4:5], v[168:169] op_sel_hi:[1,0,1]
	v_pk_fma_f32 v[104:105], v[8:9], v[4:5], v[104:105] op_sel_hi:[1,0,1]
	v_mov_b32_e32 v4, v103
	v_pk_fma_f32 v[176:177], v[6:7], v[26:27], v[176:177] op_sel_hi:[1,0,1]
	v_pk_fma_f32 v[102:103], v[10:11], v[4:5], v[174:175] op_sel_hi:[1,0,1]
	v_pk_fma_f32 v[156:157], v[8:9], v[4:5], v[156:157] op_sel_hi:[1,0,1]
	v_mov_b32_e32 v4, v27
	v_pk_fma_f32 v[178:179], v[6:7], v[186:187], v[178:179] op_sel_hi:[1,0,1]
	v_pk_fma_f32 v[26:27], v[10:11], v[4:5], v[176:177] op_sel_hi:[1,0,1]
	v_pk_fma_f32 v[158:159], v[8:9], v[4:5], v[158:159] op_sel_hi:[1,0,1]
	v_mov_b32_e32 v4, v187
	v_pk_fma_f32 v[180:181], v[6:7], v[188:189], v[180:181] op_sel_hi:[1,0,1]
	v_pk_fma_f32 v[168:169], v[10:11], v[4:5], v[178:179] op_sel_hi:[1,0,1]
	v_pk_fma_f32 v[160:161], v[8:9], v[4:5], v[160:161] op_sel_hi:[1,0,1]
	v_mov_b32_e32 v4, v189
	v_pk_fma_f32 v[182:183], v[6:7], v[190:191], v[182:183] op_sel_hi:[1,0,1]
	v_pk_fma_f32 v[174:175], v[10:11], v[4:5], v[180:181] op_sel_hi:[1,0,1]
	v_pk_fma_f32 v[162:163], v[8:9], v[4:5], v[162:163] op_sel_hi:[1,0,1]
	v_mov_b32_e32 v4, v191
	v_pk_fma_f32 v[184:185], v[6:7], v[192:193], v[184:185] op_sel_hi:[1,0,1]
	v_pk_fma_f32 v[2:3], v[6:7], v[194:195], v[2:3] op_sel_hi:[1,0,1]
	v_lshl_add_u64 v[6:7], v[100:101], 0, v[50:51]
	v_pk_fma_f32 v[176:177], v[10:11], v[4:5], v[182:183] op_sel_hi:[1,0,1]
	v_pk_fma_f32 v[164:165], v[8:9], v[4:5], v[164:165] op_sel_hi:[1,0,1]
	v_mov_b32_e32 v4, v193
	global_load_dwordx4 v[12:15], v[6:7], off
	v_pk_fma_f32 v[178:179], v[10:11], v[4:5], v[184:185] op_sel_hi:[1,0,1]
	v_pk_fma_f32 v[166:167], v[8:9], v[4:5], v[166:167] op_sel_hi:[1,0,1]
	v_lshl_add_u64 v[4:5], v[100:101], 0, v[52:53]
	global_load_dwordx4 v[4:7], v[4:5], off
	v_mov_b32_e32 v182, v195
	ds_read2_b32 v[180:181], v126 offset0:128 offset1:160
	v_pk_fma_f32 v[2:3], v[10:11], v[182:183], v[2:3] op_sel_hi:[1,0,1]
	ds_read2_b32 v[184:185], v79 offset0:128 offset1:160
	v_pk_fma_f32 v[0:1], v[8:9], v[182:183], v[0:1] op_sel_hi:[1,0,1]
	ds_read2_b32 v[182:183], v77 offset0:128 offset1:160
	ds_read2_b32 v[186:187], v75 offset0:128 offset1:160
	ds_read2_b32 v[188:189], v73 offset0:128 offset1:160
	ds_read2_b32 v[190:191], v71 offset0:128 offset1:160
	ds_read2_b32 v[192:193], v69 offset0:128 offset1:160
	ds_read2_b32 v[194:195], v81 offset0:128 offset1:160
	s_waitcnt vmcnt(3) lgkmcnt(7)
; __device__ __forceinline__ void p0_mod_item(const Params& p, LAS unsigned char* lds, int item) {
;     ...
; #pragma unroll 32
;     for (int pass = 0; pass < 32; ++pass) { const int i = pass * 32 + rs; const f32x4 w = *(const f32x4*)(p.w_ada + (size_t)i * NMOD + j0 + 4 * l16);
; #pragma unroll
;         for (int b = 0; b < 8; ++b) acc[b] += cs[b * DM + i] * w; }
	v_pk_fma_f32 v[24:25], v[22:23], v[180:181], v[24:25] op_sel_hi:[1,0,1]
	v_pk_fma_f32 v[104:105], v[20:21], v[180:181], v[104:105] op_sel_hi:[1,0,1]
	s_waitcnt lgkmcnt(6)
	v_pk_fma_f32 v[156:157], v[20:21], v[184:185], v[156:157] op_sel_hi:[1,0,1]
	s_waitcnt lgkmcnt(5)
	v_pk_fma_f32 v[158:159], v[20:21], v[182:183], v[158:159] op_sel_hi:[1,0,1]
	s_waitcnt lgkmcnt(4)
	v_pk_fma_f32 v[160:161], v[20:21], v[186:187], v[160:161] op_sel_hi:[1,0,1]
	s_waitcnt lgkmcnt(3)
	v_pk_fma_f32 v[162:163], v[20:21], v[188:189], v[162:163] op_sel_hi:[1,0,1]
	s_waitcnt lgkmcnt(2)
	v_pk_fma_f32 v[164:165], v[20:21], v[190:191], v[164:165] op_sel_hi:[1,0,1]
	s_waitcnt lgkmcnt(1)
	v_pk_fma_f32 v[166:167], v[20:21], v[192:193], v[166:167] op_sel_hi:[1,0,1]
	s_waitcnt lgkmcnt(0)
	v_pk_fma_f32 v[0:1], v[20:21], v[194:195], v[0:1] op_sel_hi:[1,0,1]
	v_mov_b32_e32 v20, v181
	v_lshl_add_u64 v[8:9], v[100:101], 0, v[54:55]
	v_pk_fma_f32 v[102:103], v[22:23], v[184:185], v[102:103] op_sel_hi:[1,0,1]
	v_pk_fma_f32 v[26:27], v[22:23], v[182:183], v[26:27] op_sel_hi:[1,0,1]
	v_pk_fma_f32 v[168:169], v[22:23], v[186:187], v[168:169] op_sel_hi:[1,0,1]
	v_pk_fma_f32 v[174:175], v[22:23], v[188:189], v[174:175] op_sel_hi:[1,0,1]
	v_pk_fma_f32 v[176:177], v[22:23], v[190:191], v[176:177] op_sel_hi:[1,0,1]
	v_pk_fma_f32 v[178:179], v[22:23], v[192:193], v[178:179] op_sel_hi:[1,0,1]
	v_pk_fma_f32 v[2:3], v[22:23], v[194:195], v[2:3] op_sel_hi:[1,0,1]
	global_load_dwordx4 v[8:11], v[8:9], off
	s_waitcnt vmcnt(3)
	v_pk_fma_f32 v[22:23], v[18:19], v[20:21], v[24:25] op_sel_hi:[1,0,1]
	v_mov_b32_e32 v24, v185
	v_pk_fma_f32 v[20:21], v[16:17], v[20:21], v[104:105] op_sel_hi:[1,0,1]
	v_pk_fma_f32 v[102:103], v[18:19], v[24:25], v[102:103] op_sel_hi:[1,0,1]
	v_pk_fma_f32 v[24:25], v[16:17], v[24:25], v[156:157] op_sel_hi:[1,0,1]
	v_mov_b32_e32 v104, v183
	v_mov_b32_e32 v156, v187
	v_pk_fma_f32 v[26:27], v[18:19], v[104:105], v[26:27] op_sel_hi:[1,0,1]
	v_pk_fma_f32 v[104:105], v[16:17], v[104:105], v[158:159] op_sel_hi:[1,0,1]
	v_pk_fma_f32 v[158:159], v[18:19], v[156:157], v[168:169] op_sel_hi:[1,0,1]
	v_pk_fma_f32 v[156:157], v[16:17], v[156:157], v[160:161] op_sel_hi:[1,0,1]
	v_mov_b32_e32 v160, v189
	v_pk_fma_f32 v[168:169], v[18:19], v[160:161], v[174:175] op_sel_hi:[1,0,1]
	v_pk_fma_f32 v[160:161], v[16:17], v[160:161], v[162:163] op_sel_hi:[1,0,1]
	v_mov_b32_e32 v162, v191
	v_pk_fma_f32 v[174:175], v[18:19], v[162:163], v[176:177] op_sel_hi:[1,0,1]
	v_pk_fma_f32 v[162:163], v[16:17], v[162:163], v[164:165] op_sel_hi:[1,0,1]
	v_mov_b32_e32 v164, v193
	v_pk_fma_f32 v[176:177], v[18:19], v[164:165], v[178:179] op_sel_hi:[1,0,1]
	v_mov_b32_e32 v178, v195
	v_pk_fma_f32 v[164:165], v[16:17], v[164:165], v[166:167] op_sel_hi:[1,0,1]
	v_pk_fma_f32 v[16:17], v[16:17], v[178:179], v[0:1] op_sel_hi:[1,0,1]
	v_lshl_add_u64 v[0:1], v[100:101], 0, v[56:57]
	v_pk_fma_f32 v[18:19], v[18:19], v[178:179], v[2:3] op_sel_hi:[1,0,1]
	global_load_dwordx4 v[0:3], v[0:1], off
	ds_read2_b32 v[166:167], v126 offset0:192 offset1:224
	ds_read2_b32 v[180:181], v79 offset0:192 offset1:224
	ds_read2_b32 v[178:179], v77 offset0:192 offset1:224
	ds_read2_b32 v[182:183], v75 offset0:192 offset1:224
	ds_read2_b32 v[184:185], v73 offset0:192 offset1:224
	ds_read2_b32 v[186:187], v71 offset0:192 offset1:224
	ds_read2_b32 v[188:189], v69 offset0:192 offset1:224
	ds_read2_b32 v[190:191], v81 offset0:192 offset1:224
	v_add_u32_e32 v71, 0x2400, v126
	v_add_u32_e32 v73, 0x3400, v126
	v_mov_b32_e32 v69, v29
	v_mov_b32_e32 v75, v29
	v_mov_b32_e32 v77, v29
	v_mov_b32_e32 v79, v29
	v_mov_b32_e32 v81, v29
	s_waitcnt vmcnt(3) lgkmcnt(7)
	v_pk_fma_f32 v[22:23], v[14:15], v[166:167], v[22:23] op_sel_hi:[1,0,1]
	v_pk_fma_f32 v[20:21], v[12:13], v[166:167], v[20:21] op_sel_hi:[1,0,1]
	s_waitcnt lgkmcnt(6)
	v_pk_fma_f32 v[102:103], v[14:15], v[180:181], v[102:103] op_sel_hi:[1,0,1]
	s_waitcnt lgkmcnt(5)
	v_pk_fma_f32 v[26:27], v[14:15], v[178:179], v[26:27] op_sel_hi:[1,0,1]
	s_waitcnt lgkmcnt(4)
	v_pk_fma_f32 v[158:159], v[14:15], v[182:183], v[158:159] op_sel_hi:[1,0,1]
	s_waitcnt lgkmcnt(3)
	v_pk_fma_f32 v[168:169], v[14:15], v[184:185], v[168:169] op_sel_hi:[1,0,1]
	s_waitcnt lgkmcnt(2)
	v_pk_fma_f32 v[174:175], v[14:15], v[186:187], v[174:175] op_sel_hi:[1,0,1]
	s_waitcnt lgkmcnt(1)
	v_pk_fma_f32 v[176:177], v[14:15], v[188:189], v[176:177] op_sel_hi:[1,0,1]
	s_waitcnt lgkmcnt(0)
	v_pk_fma_f32 v[18:19], v[14:15], v[190:191], v[18:19] op_sel_hi:[1,0,1]
	v_mov_b32_e32 v14, v167
	v_pk_fma_f32 v[24:25], v[12:13], v[180:181], v[24:25] op_sel_hi:[1,0,1]
	s_waitcnt vmcnt(2)
	v_pk_fma_f32 v[22:23], v[6:7], v[14:15], v[22:23] op_sel_hi:[1,0,1]
	v_pk_fma_f32 v[20:21], v[4:5], v[14:15], v[20:21] op_sel_hi:[1,0,1]
	v_mov_b32_e32 v14, v181
	v_pk_fma_f32 v[104:105], v[12:13], v[178:179], v[104:105] op_sel_hi:[1,0,1]
	v_pk_fma_f32 v[102:103], v[6:7], v[14:15], v[102:103] op_sel_hi:[1,0,1]
	v_pk_fma_f32 v[24:25], v[4:5], v[14:15], v[24:25] op_sel_hi:[1,0,1]
	v_mov_b32_e32 v14, v179
	v_pk_fma_f32 v[166:167], v[6:7], v[14:15], v[26:27] op_sel_hi:[1,0,1]
	v_pk_fma_f32 v[104:105], v[4:5], v[14:15], v[104:105] op_sel_hi:[1,0,1]
	v_lshl_add_u64 v[14:15], v[100:101], 0, v[58:59]
	v_pk_fma_f32 v[156:157], v[12:13], v[182:183], v[156:157] op_sel_hi:[1,0,1]
	v_pk_fma_f32 v[160:161], v[12:13], v[184:185], v[160:161] op_sel_hi:[1,0,1]
	v_pk_fma_f32 v[162:163], v[12:13], v[186:187], v[162:163] op_sel_hi:[1,0,1]
	v_pk_fma_f32 v[164:165], v[12:13], v[188:189], v[164:165] op_sel_hi:[1,0,1]
	v_pk_fma_f32 v[12:13], v[12:13], v[190:191], v[16:17] op_sel_hi:[1,0,1]
	global_load_dwordx4 v[14:17], v[14:15], off
	v_mov_b32_e32 v26, v183
	v_pk_fma_f32 v[158:159], v[6:7], v[26:27], v[158:159] op_sel_hi:[1,0,1]
	v_pk_fma_f32 v[156:157], v[4:5], v[26:27], v[156:157] op_sel_hi:[1,0,1]
	v_mov_b32_e32 v26, v185
	v_pk_fma_f32 v[168:169], v[6:7], v[26:27], v[168:169] op_sel_hi:[1,0,1]
	v_pk_fma_f32 v[160:161], v[4:5], v[26:27], v[160:161] op_sel_hi:[1,0,1]
	v_mov_b32_e32 v26, v187
	v_pk_fma_f32 v[174:175], v[6:7], v[26:27], v[174:175] op_sel_hi:[1,0,1]
	v_pk_fma_f32 v[162:163], v[4:5], v[26:27], v[162:163] op_sel_hi:[1,0,1]
	v_mov_b32_e32 v26, v189
	v_pk_fma_f32 v[176:177], v[6:7], v[26:27], v[176:177] op_sel_hi:[1,0,1]
	v_pk_fma_f32 v[164:165], v[4:5], v[26:27], v[164:165] op_sel_hi:[1,0,1]
	v_add_u32_e32 v27, 0x1400, v126
	v_add_u32_e32 v26, 0x400, v126
	ds_read2_b32 v[182:183], v27 offset1:32
	ds_read2_b32 v[180:181], v26 offset1:32
	v_mov_b32_e32 v178, v191
	v_pk_fma_f32 v[12:13], v[4:5], v[178:179], v[12:13] op_sel_hi:[1,0,1]
	v_lshl_add_u64 v[4:5], v[100:101], 0, v[60:61]
	v_pk_fma_f32 v[18:19], v[6:7], v[178:179], v[18:19] op_sel_hi:[1,0,1]
	global_load_dwordx4 v[4:7], v[4:5], off
	s_waitcnt vmcnt(3) lgkmcnt(1)
; __device__ __forceinline__ void p0_mod_item(const Params& p, LAS unsigned char* lds, int item) {
;     ...
; #pragma unroll 32
;     for (int pass = 0; pass < 32; ++pass) { const int i = pass * 32 + rs; const f32x4 w = *(const f32x4*)(p.w_ada + (size_t)i * NMOD + j0 + 4 * l16);
; #pragma unroll
;         for (int b = 0; b < 8; ++b) acc[b] += cs[b * DM + i] * w; }
	v_pk_fma_f32 v[184:185], v[8:9], v[182:183], v[24:25] op_sel_hi:[1,0,1]
	v_add_u32_e32 v25, 0x7400, v126
	s_waitcnt lgkmcnt(0)
	v_pk_fma_f32 v[178:179], v[10:11], v[180:181], v[22:23] op_sel_hi:[1,0,1]
	v_add_u32_e32 v22, 0x4400, v126
	v_add_u32_e32 v23, 0x5400, v126
	v_add_u32_e32 v24, 0x6400, v126
	ds_read2_b32 v[196:197], v25 offset1:32
	ds_read2_b32 v[186:187], v71 offset1:32
	ds_read2_b32 v[188:189], v73 offset1:32
	ds_read2_b32 v[190:191], v22 offset1:32
	ds_read2_b32 v[192:193], v23 offset1:32
	ds_read2_b32 v[194:195], v24 offset1:32
	v_pk_fma_f32 v[20:21], v[8:9], v[180:181], v[20:21] op_sel_hi:[1,0,1]
	s_waitcnt lgkmcnt(5)
	v_pk_fma_f32 v[198:199], v[10:11], v[196:197], v[18:19] op_sel_hi:[1,0,1]
	v_mov_b32_e32 v18, v181
	v_pk_fma_f32 v[102:103], v[10:11], v[182:183], v[102:103] op_sel_hi:[1,0,1]
	s_waitcnt lgkmcnt(4)
	v_pk_fma_f32 v[166:167], v[10:11], v[186:187], v[166:167] op_sel_hi:[1,0,1]
	s_waitcnt lgkmcnt(3)
	v_pk_fma_f32 v[158:159], v[10:11], v[188:189], v[158:159] op_sel_hi:[1,0,1]
	s_waitcnt lgkmcnt(2)
	v_pk_fma_f32 v[168:169], v[10:11], v[190:191], v[168:169] op_sel_hi:[1,0,1]
	s_waitcnt lgkmcnt(1)
	v_pk_fma_f32 v[174:175], v[10:11], v[192:193], v[174:175] op_sel_hi:[1,0,1]
	s_waitcnt lgkmcnt(0)
	v_pk_fma_f32 v[176:177], v[10:11], v[194:195], v[176:177] op_sel_hi:[1,0,1]
	v_lshl_add_u64 v[10:11], v[100:101], 0, v[62:63]
	s_waitcnt vmcnt(2)
	v_pk_fma_f32 v[178:179], v[2:3], v[18:19], v[178:179] op_sel_hi:[1,0,1]
	v_pk_fma_f32 v[180:181], v[0:1], v[18:19], v[20:21] op_sel_hi:[1,0,1]
	v_mov_b32_e32 v18, v183
	v_pk_fma_f32 v[104:105], v[8:9], v[186:187], v[104:105] op_sel_hi:[1,0,1]
	v_pk_fma_f32 v[156:157], v[8:9], v[188:189], v[156:157] op_sel_hi:[1,0,1]
	v_pk_fma_f32 v[160:161], v[8:9], v[190:191], v[160:161] op_sel_hi:[1,0,1]
	v_pk_fma_f32 v[162:163], v[8:9], v[192:193], v[162:163] op_sel_hi:[1,0,1]
	v_pk_fma_f32 v[164:165], v[8:9], v[194:195], v[164:165] op_sel_hi:[1,0,1]
	v_pk_fma_f32 v[8:9], v[8:9], v[196:197], v[12:13] op_sel_hi:[1,0,1]
	global_load_dwordx4 v[10:13], v[10:11], off
	v_pk_fma_f32 v[102:103], v[2:3], v[18:19], v[102:103] op_sel_hi:[1,0,1]
	v_pk_fma_f32 v[182:183], v[0:1], v[18:19], v[184:185] op_sel_hi:[1,0,1]
	v_mov_b32_e32 v18, v187
	v_pk_fma_f32 v[166:167], v[2:3], v[18:19], v[166:167] op_sel_hi:[1,0,1]
	v_pk_fma_f32 v[104:105], v[0:1], v[18:19], v[104:105] op_sel_hi:[1,0,1]
	v_mov_b32_e32 v18, v189
	v_pk_fma_f32 v[158:159], v[2:3], v[18:19], v[158:159] op_sel_hi:[1,0,1]
	v_pk_fma_f32 v[156:157], v[0:1], v[18:19], v[156:157] op_sel_hi:[1,0,1]
	v_mov_b32_e32 v18, v191
	v_pk_fma_f32 v[168:169], v[2:3], v[18:19], v[168:169] op_sel_hi:[1,0,1]
	v_pk_fma_f32 v[160:161], v[0:1], v[18:19], v[160:161] op_sel_hi:[1,0,1]
	v_mov_b32_e32 v18, v193
	v_pk_fma_f32 v[174:175], v[2:3], v[18:19], v[174:175] op_sel_hi:[1,0,1]
	v_pk_fma_f32 v[162:163], v[0:1], v[18:19], v[162:163] op_sel_hi:[1,0,1]
	v_mov_b32_e32 v18, v195
	v_pk_fma_f32 v[176:177], v[2:3], v[18:19], v[176:177] op_sel_hi:[1,0,1]
	v_pk_fma_f32 v[164:165], v[0:1], v[18:19], v[164:165] op_sel_hi:[1,0,1]
	v_lshl_add_u64 v[18:19], v[100:101], 0, v[64:65]
	global_load_dwordx4 v[18:21], v[18:19], off
	ds_read2_b32 v[184:185], v26 offset0:64 offset1:96
	v_mov_b32_e32 v186, v197
	v_pk_fma_f32 v[2:3], v[2:3], v[186:187], v[198:199] op_sel_hi:[1,0,1]
	ds_read2_b32 v[188:189], v27 offset0:64 offset1:96
	v_pk_fma_f32 v[0:1], v[0:1], v[186:187], v[8:9] op_sel_hi:[1,0,1]
	ds_read2_b32 v[186:187], v73 offset0:64 offset1:96
	ds_read2_b32 v[190:191], v22 offset0:64 offset1:96
	s_waitcnt vmcnt(3) lgkmcnt(3)
	v_pk_fma_f32 v[8:9], v[16:17], v[184:185], v[178:179] op_sel_hi:[1,0,1]
	ds_read2_b32 v[178:179], v71 offset0:64 offset1:96
	ds_read2_b32 v[192:193], v23 offset0:64 offset1:96
	ds_read2_b32 v[194:195], v24 offset0:64 offset1:96
	ds_read2_b32 v[196:197], v25 offset0:64 offset1:96
	v_pk_fma_f32 v[180:181], v[14:15], v[184:185], v[180:181] op_sel_hi:[1,0,1]
	s_waitcnt lgkmcnt(6)
	v_pk_fma_f32 v[182:183], v[14:15], v[188:189], v[182:183] op_sel_hi:[1,0,1]
	s_waitcnt lgkmcnt(3)
	v_pk_fma_f32 v[104:105], v[14:15], v[178:179], v[104:105] op_sel_hi:[1,0,1]
	v_pk_fma_f32 v[156:157], v[14:15], v[186:187], v[156:157] op_sel_hi:[1,0,1]
	v_pk_fma_f32 v[160:161], v[14:15], v[190:191], v[160:161] op_sel_hi:[1,0,1]
	s_waitcnt lgkmcnt(2)
	v_pk_fma_f32 v[162:163], v[14:15], v[192:193], v[162:163] op_sel_hi:[1,0,1]
	s_waitcnt lgkmcnt(1)
	v_pk_fma_f32 v[164:165], v[14:15], v[194:195], v[164:165] op_sel_hi:[1,0,1]
	s_waitcnt lgkmcnt(0)
	v_pk_fma_f32 v[0:1], v[14:15], v[196:197], v[0:1] op_sel_hi:[1,0,1]
	v_lshl_add_u64 v[14:15], v[100:101], 0, v[66:67]
	v_pk_fma_f32 v[102:103], v[16:17], v[188:189], v[102:103] op_sel_hi:[1,0,1]
	v_pk_fma_f32 v[166:167], v[16:17], v[178:179], v[166:167] op_sel_hi:[1,0,1]
	v_pk_fma_f32 v[158:159], v[16:17], v[186:187], v[158:159] op_sel_hi:[1,0,1]
	v_pk_fma_f32 v[168:169], v[16:17], v[190:191], v[168:169] op_sel_hi:[1,0,1]
	v_pk_fma_f32 v[174:175], v[16:17], v[192:193], v[174:175] op_sel_hi:[1,0,1]
	v_pk_fma_f32 v[176:177], v[16:17], v[194:195], v[176:177] op_sel_hi:[1,0,1]
	v_pk_fma_f32 v[2:3], v[16:17], v[196:197], v[2:3] op_sel_hi:[1,0,1]
	global_load_dwordx4 v[14:17], v[14:15], off
	v_mov_b32_e32 v178, v185
	s_waitcnt vmcnt(3)
; __device__ __forceinline__ void p0_mod_item(const Params& p, LAS unsigned char* lds, int item) {
;     ...
; #pragma unroll 32
;     for (int pass = 0; pass < 32; ++pass) { const int i = pass * 32 + rs; const f32x4 w = *(const f32x4*)(p.w_ada + (size_t)i * NMOD + j0 + 4 * l16);
; #pragma unroll
;         for (int b = 0; b < 8; ++b) acc[b] += cs[b * DM + i] * w; }
	v_pk_fma_f32 v[184:185], v[6:7], v[178:179], v[8:9] op_sel_hi:[1,0,1]
	v_mov_b32_e32 v8, v189
	v_pk_fma_f32 v[102:103], v[6:7], v[8:9], v[102:103] op_sel_hi:[1,0,1]
	v_pk_fma_f32 v[182:183], v[4:5], v[8:9], v[182:183] op_sel_hi:[1,0,1]
	v_mov_b32_e32 v8, v179
	v_pk_fma_f32 v[166:167], v[6:7], v[8:9], v[166:167] op_sel_hi:[1,0,1]
	v_pk_fma_f32 v[104:105], v[4:5], v[8:9], v[104:105] op_sel_hi:[1,0,1]
	v_mov_b32_e32 v8, v187
	ds_read2_b32 v[186:187], v26 offset0:128 offset1:160
	v_pk_fma_f32 v[158:159], v[6:7], v[8:9], v[158:159] op_sel_hi:[1,0,1]
	v_pk_fma_f32 v[156:157], v[4:5], v[8:9], v[156:157] op_sel_hi:[1,0,1]
	v_mov_b32_e32 v8, v191
	v_pk_fma_f32 v[168:169], v[6:7], v[8:9], v[168:169] op_sel_hi:[1,0,1]
	v_pk_fma_f32 v[160:161], v[4:5], v[8:9], v[160:161] op_sel_hi:[1,0,1]
	v_mov_b32_e32 v8, v193
	v_pk_fma_f32 v[180:181], v[4:5], v[178:179], v[180:181] op_sel_hi:[1,0,1]
	v_pk_fma_f32 v[174:175], v[6:7], v[8:9], v[174:175] op_sel_hi:[1,0,1]
	v_pk_fma_f32 v[162:163], v[4:5], v[8:9], v[162:163] op_sel_hi:[1,0,1]
	v_mov_b32_e32 v8, v195
	v_mov_b32_e32 v178, v197
	v_pk_fma_f32 v[176:177], v[6:7], v[8:9], v[176:177] op_sel_hi:[1,0,1]
	v_pk_fma_f32 v[2:3], v[6:7], v[178:179], v[2:3] op_sel_hi:[1,0,1]
	v_lshl_add_u64 v[6:7], v[100:101], 0, v[28:29]
	v_pk_fma_f32 v[164:165], v[4:5], v[8:9], v[164:165] op_sel_hi:[1,0,1]
	global_load_dwordx4 v[6:9], v[6:7], off
	ds_read2_b32 v[188:189], v27 offset0:128 offset1:160
	v_pk_fma_f32 v[0:1], v[4:5], v[178:179], v[0:1] op_sel_hi:[1,0,1]
	ds_read2_b32 v[178:179], v71 offset0:128 offset1:160
	ds_read2_b32 v[190:191], v22 offset0:128 offset1:160
	ds_read2_b32 v[192:193], v23 offset0:128 offset1:160
	s_waitcnt vmcnt(3) lgkmcnt(4)
	v_pk_fma_f32 v[4:5], v[12:13], v[186:187], v[184:185] op_sel_hi:[1,0,1]
	ds_read2_b32 v[184:185], v73 offset0:128 offset1:160
	ds_read2_b32 v[194:195], v24 offset0:128 offset1:160
	ds_read2_b32 v[196:197], v25 offset0:128 offset1:160
	v_pk_fma_f32 v[180:181], v[10:11], v[186:187], v[180:181] op_sel_hi:[1,0,1]
	s_waitcnt lgkmcnt(6)
	v_pk_fma_f32 v[182:183], v[10:11], v[188:189], v[182:183] op_sel_hi:[1,0,1]
	s_waitcnt lgkmcnt(5)
	v_pk_fma_f32 v[104:105], v[10:11], v[178:179], v[104:105] op_sel_hi:[1,0,1]
	s_waitcnt lgkmcnt(2)
	v_pk_fma_f32 v[156:157], v[10:11], v[184:185], v[156:157] op_sel_hi:[1,0,1]
	v_pk_fma_f32 v[160:161], v[10:11], v[190:191], v[160:161] op_sel_hi:[1,0,1]
	v_pk_fma_f32 v[162:163], v[10:11], v[192:193], v[162:163] op_sel_hi:[1,0,1]
	s_waitcnt lgkmcnt(1)
	v_pk_fma_f32 v[164:165], v[10:11], v[194:195], v[164:165] op_sel_hi:[1,0,1]
	s_waitcnt lgkmcnt(0)
	v_pk_fma_f32 v[0:1], v[10:11], v[196:197], v[0:1] op_sel_hi:[1,0,1]
	v_mov_b32_e32 v10, v187
	v_pk_fma_f32 v[102:103], v[12:13], v[188:189], v[102:103] op_sel_hi:[1,0,1]
	v_pk_fma_f32 v[166:167], v[12:13], v[178:179], v[166:167] op_sel_hi:[1,0,1]
	v_pk_fma_f32 v[158:159], v[12:13], v[184:185], v[158:159] op_sel_hi:[1,0,1]
	v_pk_fma_f32 v[168:169], v[12:13], v[190:191], v[168:169] op_sel_hi:[1,0,1]
	v_pk_fma_f32 v[174:175], v[12:13], v[192:193], v[174:175] op_sel_hi:[1,0,1]
	v_pk_fma_f32 v[176:177], v[12:13], v[194:195], v[176:177] op_sel_hi:[1,0,1]
	s_waitcnt vmcnt(2)
	v_pk_fma_f32 v[4:5], v[20:21], v[10:11], v[4:5] op_sel_hi:[1,0,1]
	v_pk_fma_f32 v[180:181], v[18:19], v[10:11], v[180:181] op_sel_hi:[1,0,1]
	v_lshl_add_u64 v[10:11], v[100:101], 0, v[68:69]
	v_pk_fma_f32 v[2:3], v[12:13], v[196:197], v[2:3] op_sel_hi:[1,0,1]
	global_load_dwordx4 v[10:13], v[10:11], off
	v_mov_b32_e32 v178, v189
	v_pk_fma_f32 v[102:103], v[20:21], v[178:179], v[102:103] op_sel_hi:[1,0,1]
	v_pk_fma_f32 v[182:183], v[18:19], v[178:179], v[182:183] op_sel_hi:[1,0,1]
	v_mov_b32_e32 v178, v179
	v_pk_fma_f32 v[166:167], v[20:21], v[178:179], v[166:167] op_sel_hi:[1,0,1]
	v_pk_fma_f32 v[104:105], v[18:19], v[178:179], v[104:105] op_sel_hi:[1,0,1]
	v_mov_b32_e32 v178, v185
	v_pk_fma_f32 v[158:159], v[20:21], v[178:179], v[158:159] op_sel_hi:[1,0,1]
	v_pk_fma_f32 v[156:157], v[18:19], v[178:179], v[156:157] op_sel_hi:[1,0,1]
	v_mov_b32_e32 v178, v191
	v_pk_fma_f32 v[168:169], v[20:21], v[178:179], v[168:169] op_sel_hi:[1,0,1]
	v_pk_fma_f32 v[160:161], v[18:19], v[178:179], v[160:161] op_sel_hi:[1,0,1]
	v_mov_b32_e32 v178, v193
	v_pk_fma_f32 v[174:175], v[20:21], v[178:179], v[174:175] op_sel_hi:[1,0,1]
	v_pk_fma_f32 v[162:163], v[18:19], v[178:179], v[162:163] op_sel_hi:[1,0,1]
	v_mov_b32_e32 v178, v195
	v_pk_fma_f32 v[176:177], v[20:21], v[178:179], v[176:177] op_sel_hi:[1,0,1]
	v_pk_fma_f32 v[164:165], v[18:19], v[178:179], v[164:165] op_sel_hi:[1,0,1]
	ds_read2_b32 v[178:179], v26 offset0:192 offset1:224
	ds_read2_b32 v[184:185], v27 offset0:192 offset1:224
	v_mov_b32_e32 v26, v197
	v_pk_fma_f32 v[20:21], v[20:21], v[26:27], v[2:3] op_sel_hi:[1,0,1]
	v_pk_fma_f32 v[18:19], v[18:19], v[26:27], v[0:1] op_sel_hi:[1,0,1]
	v_add_u32_e32 v69, 0x4800, v126
	s_waitcnt vmcnt(2) lgkmcnt(1)
	v_pk_fma_f32 v[26:27], v[14:15], v[178:179], v[180:181] op_sel_hi:[1,0,1]
	s_waitcnt lgkmcnt(0)
	v_pk_fma_f32 v[180:181], v[14:15], v[184:185], v[182:183] op_sel_hi:[1,0,1]
	ds_read2_b32 v[182:183], v71 offset0:192 offset1:224
	ds_read2_b32 v[186:187], v73 offset0:192 offset1:224
	v_mov_b32_e32 v71, v29
	v_lshl_add_u64 v[0:1], v[100:101], 0, v[70:71]
	global_load_dwordx4 v[0:3], v[0:1], off
	ds_read2_b32 v[188:189], v22 offset0:192 offset1:224
	ds_read2_b32 v[22:23], v23 offset0:192 offset1:224
	ds_read2_b32 v[190:191], v24 offset0:192 offset1:224
	ds_read2_b32 v[24:25], v25 offset0:192 offset1:224
	v_pk_fma_f32 v[4:5], v[16:17], v[178:179], v[4:5] op_sel_hi:[1,0,1]
	s_waitcnt lgkmcnt(3)
; __device__ __forceinline__ void p0_mod_item(const Params& p, LAS unsigned char* lds, int item) {
;     ...
; #pragma unroll 32
;     for (int pass = 0; pass < 32; ++pass) { const int i = pass * 32 + rs; const f32x4 w = *(const f32x4*)(p.w_ada + (size_t)i * NMOD + j0 + 4 * l16);
; #pragma unroll
;         for (int b = 0; b < 8; ++b) acc[b] += cs[b * DM + i] * w; }
	v_pk_fma_f32 v[168:169], v[16:17], v[188:189], v[168:169] op_sel_hi:[1,0,1]
	v_pk_fma_f32 v[160:161], v[14:15], v[188:189], v[160:161] op_sel_hi:[1,0,1]
	s_waitcnt lgkmcnt(2)
	v_pk_fma_f32 v[174:175], v[16:17], v[22:23], v[174:175] op_sel_hi:[1,0,1]
	v_pk_fma_f32 v[162:163], v[14:15], v[22:23], v[162:163] op_sel_hi:[1,0,1]
	v_mov_b32_e32 v22, v189
	s_waitcnt lgkmcnt(1)
	v_pk_fma_f32 v[176:177], v[16:17], v[190:191], v[176:177] op_sel_hi:[1,0,1]
	s_waitcnt lgkmcnt(0)
	v_pk_fma_f32 v[20:21], v[16:17], v[24:25], v[20:21] op_sel_hi:[1,0,1]
	v_pk_fma_f32 v[18:19], v[14:15], v[24:25], v[18:19] op_sel_hi:[1,0,1]
	v_mov_b32_e32 v24, v191
	v_pk_fma_f32 v[104:105], v[14:15], v[182:183], v[104:105] op_sel_hi:[1,0,1]
	v_pk_fma_f32 v[156:157], v[14:15], v[186:187], v[156:157] op_sel_hi:[1,0,1]
	v_pk_fma_f32 v[164:165], v[14:15], v[190:191], v[164:165] op_sel_hi:[1,0,1]
	v_mov_b32_e32 v14, v179
	v_pk_fma_f32 v[102:103], v[16:17], v[184:185], v[102:103] op_sel_hi:[1,0,1]
	v_pk_fma_f32 v[166:167], v[16:17], v[182:183], v[166:167] op_sel_hi:[1,0,1]
	s_waitcnt vmcnt(2)
	v_pk_fma_f32 v[168:169], v[8:9], v[22:23], v[168:169] op_sel_hi:[1,0,1]
	v_pk_fma_f32 v[160:161], v[6:7], v[22:23], v[160:161] op_sel_hi:[1,0,1]
	v_mov_b32_e32 v22, v23
	v_pk_fma_f32 v[174:175], v[8:9], v[22:23], v[174:175] op_sel_hi:[1,0,1]
	v_pk_fma_f32 v[22:23], v[6:7], v[22:23], v[162:163] op_sel_hi:[1,0,1]
	v_pk_fma_f32 v[162:163], v[8:9], v[24:25], v[176:177] op_sel_hi:[1,0,1]
	ds_read2_b32 v[176:177], v87 offset1:32
	v_pk_fma_f32 v[4:5], v[8:9], v[14:15], v[4:5] op_sel_hi:[1,0,1]
	v_pk_fma_f32 v[26:27], v[6:7], v[14:15], v[26:27] op_sel_hi:[1,0,1]
	v_mov_b32_e32 v14, v185
	v_pk_fma_f32 v[102:103], v[8:9], v[14:15], v[102:103] op_sel_hi:[1,0,1]
	v_pk_fma_f32 v[178:179], v[6:7], v[14:15], v[180:181] op_sel_hi:[1,0,1]
	v_mov_b32_e32 v14, v183
	v_pk_fma_f32 v[158:159], v[16:17], v[186:187], v[158:159] op_sel_hi:[1,0,1]
	v_pk_fma_f32 v[166:167], v[8:9], v[14:15], v[166:167] op_sel_hi:[1,0,1]
	v_pk_fma_f32 v[104:105], v[6:7], v[14:15], v[104:105] op_sel_hi:[1,0,1]
	v_mov_b32_e32 v14, v187
	v_mov_b32_e32 v73, v29
	v_pk_fma_f32 v[158:159], v[8:9], v[14:15], v[158:159] op_sel_hi:[1,0,1]
	v_pk_fma_f32 v[156:157], v[6:7], v[14:15], v[156:157] op_sel_hi:[1,0,1]
	v_lshl_add_u64 v[14:15], v[100:101], 0, v[72:73]
	v_pk_fma_f32 v[164:165], v[6:7], v[24:25], v[164:165] op_sel_hi:[1,0,1]
	v_mov_b32_e32 v24, v25
	global_load_dwordx4 v[14:17], v[14:15], off
	v_pk_fma_f32 v[8:9], v[8:9], v[24:25], v[20:21] op_sel_hi:[1,0,1]
	v_pk_fma_f32 v[18:19], v[6:7], v[24:25], v[18:19] op_sel_hi:[1,0,1]
	v_add_u32_e32 v71, 0x5800, v126
	v_add_u32_e32 v73, 0x6800, v126
	ds_read2_b32 v[180:181], v89 offset1:32
	s_waitcnt vmcnt(2) lgkmcnt(1)
	v_pk_fma_f32 v[20:21], v[12:13], v[176:177], v[4:5] op_sel_hi:[1,0,1]
	v_lshl_add_u64 v[4:5], v[100:101], 0, v[74:75]
	global_load_dwordx4 v[4:7], v[4:5], off
	v_add_u32_e32 v75, 0x7800, v126
	ds_read2_b32 v[182:183], v91 offset1:32
	ds_read2_b32 v[184:185], v93 offset1:32
	ds_read2_b32 v[186:187], v69 offset1:32
	ds_read2_b32 v[188:189], v71 offset1:32
	ds_read2_b32 v[190:191], v73 offset1:32
	ds_read2_b32 v[192:193], v75 offset1:32
	s_waitcnt lgkmcnt(6)
	v_pk_fma_f32 v[102:103], v[12:13], v[180:181], v[102:103] op_sel_hi:[1,0,1]
	s_waitcnt lgkmcnt(5)
	v_pk_fma_f32 v[166:167], v[12:13], v[182:183], v[166:167] op_sel_hi:[1,0,1]
	s_waitcnt lgkmcnt(4)
	v_pk_fma_f32 v[158:159], v[12:13], v[184:185], v[158:159] op_sel_hi:[1,0,1]
	s_waitcnt lgkmcnt(3)
	v_pk_fma_f32 v[168:169], v[12:13], v[186:187], v[168:169] op_sel_hi:[1,0,1]
	s_waitcnt lgkmcnt(2)
	v_pk_fma_f32 v[174:175], v[12:13], v[188:189], v[174:175] op_sel_hi:[1,0,1]
	s_waitcnt lgkmcnt(1)
	v_pk_fma_f32 v[162:163], v[12:13], v[190:191], v[162:163] op_sel_hi:[1,0,1]
	s_waitcnt lgkmcnt(0)
	v_pk_fma_f32 v[8:9], v[12:13], v[192:193], v[8:9] op_sel_hi:[1,0,1]
	v_mov_b32_e32 v12, v177
	v_pk_fma_f32 v[24:25], v[10:11], v[176:177], v[26:27] op_sel_hi:[1,0,1]
	v_pk_fma_f32 v[178:179], v[10:11], v[180:181], v[178:179] op_sel_hi:[1,0,1]
	v_pk_fma_f32 v[104:105], v[10:11], v[182:183], v[104:105] op_sel_hi:[1,0,1]
	v_pk_fma_f32 v[156:157], v[10:11], v[184:185], v[156:157] op_sel_hi:[1,0,1]
	v_pk_fma_f32 v[160:161], v[10:11], v[186:187], v[160:161] op_sel_hi:[1,0,1]
	v_pk_fma_f32 v[22:23], v[10:11], v[188:189], v[22:23] op_sel_hi:[1,0,1]
	v_pk_fma_f32 v[164:165], v[10:11], v[190:191], v[164:165] op_sel_hi:[1,0,1]
	v_pk_fma_f32 v[10:11], v[10:11], v[192:193], v[18:19] op_sel_hi:[1,0,1]
	v_mov_b32_e32 v180, v193
	ds_read2_b32 v[192:193], v75 offset0:64 offset1:96
	s_waitcnt vmcnt(2)
	v_pk_fma_f32 v[18:19], v[2:3], v[12:13], v[20:21] op_sel_hi:[1,0,1]
	v_mov_b32_e32 v20, v181
	v_pk_fma_f32 v[102:103], v[2:3], v[20:21], v[102:103] op_sel_hi:[1,0,1]
	v_pk_fma_f32 v[176:177], v[0:1], v[20:21], v[178:179] op_sel_hi:[1,0,1]
	v_mov_b32_e32 v20, v183
	v_pk_fma_f32 v[166:167], v[2:3], v[20:21], v[166:167] op_sel_hi:[1,0,1]
	v_pk_fma_f32 v[104:105], v[0:1], v[20:21], v[104:105] op_sel_hi:[1,0,1]
	v_mov_b32_e32 v20, v185
	v_pk_fma_f32 v[158:159], v[2:3], v[20:21], v[158:159] op_sel_hi:[1,0,1]
	v_pk_fma_f32 v[156:157], v[0:1], v[20:21], v[156:157] op_sel_hi:[1,0,1]
	v_mov_b32_e32 v20, v187
	v_pk_fma_f32 v[168:169], v[2:3], v[20:21], v[168:169] op_sel_hi:[1,0,1]
	v_pk_fma_f32 v[160:161], v[0:1], v[20:21], v[160:161] op_sel_hi:[1,0,1]
	v_mov_b32_e32 v20, v189
	v_pk_fma_f32 v[12:13], v[0:1], v[12:13], v[24:25] op_sel_hi:[1,0,1]
	v_lshl_add_u64 v[24:25], v[100:101], 0, v[76:77]
	v_pk_fma_f32 v[174:175], v[2:3], v[20:21], v[174:175] op_sel_hi:[1,0,1]
	v_pk_fma_f32 v[178:179], v[0:1], v[20:21], v[22:23] op_sel_hi:[1,0,1]
	v_mov_b32_e32 v20, v191
	global_load_dwordx4 v[24:27], v[24:25], off
	v_pk_fma_f32 v[162:163], v[2:3], v[20:21], v[162:163] op_sel_hi:[1,0,1]
	v_pk_fma_f32 v[164:165], v[0:1], v[20:21], v[164:165] op_sel_hi:[1,0,1]
	v_lshl_add_u64 v[20:21], v[100:101], 0, v[78:79]
	global_load_dwordx4 v[20:23], v[20:21], off
	v_pk_fma_f32 v[2:3], v[2:3], v[180:181], v[8:9] op_sel_hi:[1,0,1]
	ds_read2_b32 v[8:9], v87 offset0:64 offset1:96
	ds_read2_b32 v[182:183], v89 offset0:64 offset1:96
	v_pk_fma_f32 v[0:1], v[0:1], v[180:181], v[10:11] op_sel_hi:[1,0,1]
	ds_read2_b32 v[180:181], v91 offset0:64 offset1:96
	ds_read2_b32 v[184:185], v93 offset0:64 offset1:96
	ds_read2_b32 v[186:187], v69 offset0:64 offset1:96
	ds_read2_b32 v[188:189], v71 offset0:64 offset1:96
	ds_read2_b32 v[190:191], v73 offset0:64 offset1:96
	s_waitcnt vmcnt(3) lgkmcnt(6)
; __device__ __forceinline__ void p0_mod_item(const Params& p, LAS unsigned char* lds, int item) {
;     ...
; #pragma unroll 32
;     for (int pass = 0; pass < 32; ++pass) { const int i = pass * 32 + rs; const f32x4 w = *(const f32x4*)(p.w_ada + (size_t)i * NMOD + j0 + 4 * l16);
; #pragma unroll
;         for (int b = 0; b < 8; ++b) acc[b] += cs[b * DM + i] * w; }
	v_pk_fma_f32 v[10:11], v[16:17], v[8:9], v[18:19] op_sel_hi:[1,0,1]
	v_pk_fma_f32 v[12:13], v[14:15], v[8:9], v[12:13] op_sel_hi:[1,0,1]
	s_waitcnt lgkmcnt(5)
	v_pk_fma_f32 v[176:177], v[14:15], v[182:183], v[176:177] op_sel_hi:[1,0,1]
	s_waitcnt lgkmcnt(4)
	v_pk_fma_f32 v[104:105], v[14:15], v[180:181], v[104:105] op_sel_hi:[1,0,1]
	s_waitcnt lgkmcnt(3)
	v_pk_fma_f32 v[156:157], v[14:15], v[184:185], v[156:157] op_sel_hi:[1,0,1]
	s_waitcnt lgkmcnt(2)
	v_pk_fma_f32 v[160:161], v[14:15], v[186:187], v[160:161] op_sel_hi:[1,0,1]
	s_waitcnt lgkmcnt(1)
	v_pk_fma_f32 v[178:179], v[14:15], v[188:189], v[178:179] op_sel_hi:[1,0,1]
	s_waitcnt lgkmcnt(0)
	v_pk_fma_f32 v[164:165], v[14:15], v[190:191], v[164:165] op_sel_hi:[1,0,1]
	v_pk_fma_f32 v[0:1], v[14:15], v[192:193], v[0:1] op_sel_hi:[1,0,1]
	v_mov_b32_e32 v8, v9
	v_lshl_add_u64 v[14:15], v[100:101], 0, v[80:81]
	v_pk_fma_f32 v[102:103], v[16:17], v[182:183], v[102:103] op_sel_hi:[1,0,1]
	v_pk_fma_f32 v[166:167], v[16:17], v[180:181], v[166:167] op_sel_hi:[1,0,1]
	v_pk_fma_f32 v[158:159], v[16:17], v[184:185], v[158:159] op_sel_hi:[1,0,1]
	v_pk_fma_f32 v[168:169], v[16:17], v[186:187], v[168:169] op_sel_hi:[1,0,1]
	v_pk_fma_f32 v[174:175], v[16:17], v[188:189], v[174:175] op_sel_hi:[1,0,1]
	v_pk_fma_f32 v[162:163], v[16:17], v[190:191], v[162:163] op_sel_hi:[1,0,1]
	v_pk_fma_f32 v[2:3], v[16:17], v[192:193], v[2:3] op_sel_hi:[1,0,1]
	global_load_dwordx4 v[16:19], v[14:15], off
	s_waitcnt vmcnt(3)
	v_pk_fma_f32 v[14:15], v[6:7], v[8:9], v[10:11] op_sel_hi:[1,0,1]
	v_pk_fma_f32 v[12:13], v[4:5], v[8:9], v[12:13] op_sel_hi:[1,0,1]
	v_mov_b32_e32 v8, v183
	v_pk_fma_f32 v[102:103], v[6:7], v[8:9], v[102:103] op_sel_hi:[1,0,1]
	v_pk_fma_f32 v[176:177], v[4:5], v[8:9], v[176:177] op_sel_hi:[1,0,1]
	v_mov_b32_e32 v8, v181
	v_pk_fma_f32 v[166:167], v[6:7], v[8:9], v[166:167] op_sel_hi:[1,0,1]
	v_pk_fma_f32 v[104:105], v[4:5], v[8:9], v[104:105] op_sel_hi:[1,0,1]
	v_mov_b32_e32 v8, v185
	v_pk_fma_f32 v[158:159], v[6:7], v[8:9], v[158:159] op_sel_hi:[1,0,1]
	v_pk_fma_f32 v[156:157], v[4:5], v[8:9], v[156:157] op_sel_hi:[1,0,1]
	v_mov_b32_e32 v8, v187
	v_pk_fma_f32 v[168:169], v[6:7], v[8:9], v[168:169] op_sel_hi:[1,0,1]
	v_pk_fma_f32 v[160:161], v[4:5], v[8:9], v[160:161] op_sel_hi:[1,0,1]
	v_mov_b32_e32 v8, v189
	v_pk_fma_f32 v[174:175], v[6:7], v[8:9], v[174:175] op_sel_hi:[1,0,1]
	v_pk_fma_f32 v[178:179], v[4:5], v[8:9], v[178:179] op_sel_hi:[1,0,1]
	v_mov_b32_e32 v8, v191
	v_pk_fma_f32 v[162:163], v[6:7], v[8:9], v[162:163] op_sel_hi:[1,0,1]
	v_pk_fma_f32 v[164:165], v[4:5], v[8:9], v[164:165] op_sel_hi:[1,0,1]
	v_lshl_add_u64 v[8:9], v[100:101], 0, v[82:83]
	global_load_dwordx4 v[8:11], v[8:9], off
	v_mov_b32_e32 v180, v193
	v_pk_fma_f32 v[2:3], v[6:7], v[180:181], v[2:3] op_sel_hi:[1,0,1]
	ds_read2_b32 v[6:7], v87 offset0:128 offset1:160
	ds_read2_b32 v[182:183], v89 offset0:128 offset1:160
	v_pk_fma_f32 v[0:1], v[4:5], v[180:181], v[0:1] op_sel_hi:[1,0,1]
	ds_read2_b32 v[180:181], v91 offset0:128 offset1:160
	ds_read2_b32 v[184:185], v93 offset0:128 offset1:160
	ds_read2_b32 v[186:187], v69 offset0:128 offset1:160
	ds_read2_b32 v[188:189], v71 offset0:128 offset1:160
	ds_read2_b32 v[190:191], v73 offset0:128 offset1:160
	ds_read2_b32 v[192:193], v75 offset0:128 offset1:160
	s_waitcnt vmcnt(3) lgkmcnt(7)
	v_pk_fma_f32 v[4:5], v[26:27], v[6:7], v[14:15] op_sel_hi:[1,0,1]
	v_pk_fma_f32 v[12:13], v[24:25], v[6:7], v[12:13] op_sel_hi:[1,0,1]
	v_mov_b32_e32 v6, v7
	s_waitcnt lgkmcnt(6)
	v_pk_fma_f32 v[102:103], v[26:27], v[182:183], v[102:103] op_sel_hi:[1,0,1]
	v_pk_fma_f32 v[176:177], v[24:25], v[182:183], v[176:177] op_sel_hi:[1,0,1]
	s_waitcnt lgkmcnt(5)
	v_pk_fma_f32 v[104:105], v[24:25], v[180:181], v[104:105] op_sel_hi:[1,0,1]
	s_waitcnt lgkmcnt(4)
	v_pk_fma_f32 v[156:157], v[24:25], v[184:185], v[156:157] op_sel_hi:[1,0,1]
	s_waitcnt lgkmcnt(3)
	v_pk_fma_f32 v[160:161], v[24:25], v[186:187], v[160:161] op_sel_hi:[1,0,1]
	s_waitcnt lgkmcnt(2)
	v_pk_fma_f32 v[178:179], v[24:25], v[188:189], v[178:179] op_sel_hi:[1,0,1]
	s_waitcnt lgkmcnt(1)
	v_pk_fma_f32 v[164:165], v[24:25], v[190:191], v[164:165] op_sel_hi:[1,0,1]
	s_waitcnt lgkmcnt(0)
	v_pk_fma_f32 v[0:1], v[24:25], v[192:193], v[0:1] op_sel_hi:[1,0,1]
	s_waitcnt vmcnt(2)
	v_pk_fma_f32 v[4:5], v[22:23], v[6:7], v[4:5] op_sel_hi:[1,0,1]
	v_pk_fma_f32 v[6:7], v[20:21], v[6:7], v[12:13] op_sel_hi:[1,0,1]
	v_lshl_add_u64 v[12:13], v[100:101], 0, v[84:85]
	v_mov_b32_e32 v24, v183
	v_pk_fma_f32 v[166:167], v[26:27], v[180:181], v[166:167] op_sel_hi:[1,0,1]
	v_pk_fma_f32 v[158:159], v[26:27], v[184:185], v[158:159] op_sel_hi:[1,0,1]
	v_pk_fma_f32 v[168:169], v[26:27], v[186:187], v[168:169] op_sel_hi:[1,0,1]
	v_pk_fma_f32 v[174:175], v[26:27], v[188:189], v[174:175] op_sel_hi:[1,0,1]
	v_pk_fma_f32 v[162:163], v[26:27], v[190:191], v[162:163] op_sel_hi:[1,0,1]
	v_pk_fma_f32 v[2:3], v[26:27], v[192:193], v[2:3] op_sel_hi:[1,0,1]
	global_load_dwordx4 v[12:15], v[12:13], off
	v_pk_fma_f32 v[26:27], v[22:23], v[24:25], v[102:103] op_sel_hi:[1,0,1]
	v_mov_b32_e32 v102, v181
	v_pk_fma_f32 v[166:167], v[22:23], v[102:103], v[166:167] op_sel_hi:[1,0,1]
	v_pk_fma_f32 v[102:103], v[20:21], v[102:103], v[104:105] op_sel_hi:[1,0,1]
	v_mov_b32_e32 v104, v185
	v_pk_fma_f32 v[158:159], v[22:23], v[104:105], v[158:159] op_sel_hi:[1,0,1]
	v_pk_fma_f32 v[104:105], v[20:21], v[104:105], v[156:157] op_sel_hi:[1,0,1]
	v_mov_b32_e32 v156, v187
	v_pk_fma_f32 v[24:25], v[20:21], v[24:25], v[176:177] op_sel_hi:[1,0,1]
	v_pk_fma_f32 v[168:169], v[22:23], v[156:157], v[168:169] op_sel_hi:[1,0,1]
	v_pk_fma_f32 v[156:157], v[20:21], v[156:157], v[160:161] op_sel_hi:[1,0,1]
	v_mov_b32_e32 v160, v189
	v_mov_b32_e32 v176, v191
	v_pk_fma_f32 v[174:175], v[22:23], v[160:161], v[174:175] op_sel_hi:[1,0,1]
	v_pk_fma_f32 v[160:161], v[20:21], v[160:161], v[178:179] op_sel_hi:[1,0,1]
	v_pk_fma_f32 v[162:163], v[22:23], v[176:177], v[162:163] op_sel_hi:[1,0,1]
	v_pk_fma_f32 v[164:165], v[20:21], v[176:177], v[164:165] op_sel_hi:[1,0,1]
	ds_read2_b32 v[176:177], v87 offset0:192 offset1:224
	v_mov_b32_e32 v178, v193
	v_mov_b32_e32 v87, v29
	v_pk_fma_f32 v[20:21], v[20:21], v[178:179], v[0:1] op_sel_hi:[1,0,1]
	v_lshl_add_u64 v[0:1], v[100:101], 0, v[86:87]
	ds_read2_b32 v[180:181], v89 offset0:192 offset1:224
	v_pk_fma_f32 v[22:23], v[22:23], v[178:179], v[2:3] op_sel_hi:[1,0,1]
	ds_read2_b32 v[178:179], v91 offset0:192 offset1:224
	ds_read2_b32 v[182:183], v93 offset0:192 offset1:224
	global_load_dwordx4 v[0:3], v[0:1], off
	ds_read2_b32 v[184:185], v69 offset0:192 offset1:224
	ds_read2_b32 v[186:187], v71 offset0:192 offset1:224
	ds_read2_b32 v[188:189], v73 offset0:192 offset1:224
	ds_read2_b32 v[190:191], v75 offset0:192 offset1:224
	s_waitcnt vmcnt(3) lgkmcnt(7)
; __device__ __forceinline__ void p0_mod_item(const Params& p, LAS unsigned char* lds, int item) {
;     ...
; #pragma unroll 32
;     for (int pass = 0; pass < 32; ++pass) { const int i = pass * 32 + rs; const f32x4 w = *(const f32x4*)(p.w_ada + (size_t)i * NMOD + j0 + 4 * l16);
; #pragma unroll
;         for (int b = 0; b < 8; ++b) acc[b] += cs[b * DM + i] * w; }
	v_pk_fma_f32 v[4:5], v[18:19], v[176:177], v[4:5] op_sel_hi:[1,0,1]
	v_pk_fma_f32 v[6:7], v[16:17], v[176:177], v[6:7] op_sel_hi:[1,0,1]
	s_waitcnt lgkmcnt(6)
	v_pk_fma_f32 v[24:25], v[16:17], v[180:181], v[24:25] op_sel_hi:[1,0,1]
	s_waitcnt lgkmcnt(5)
	v_pk_fma_f32 v[102:103], v[16:17], v[178:179], v[102:103] op_sel_hi:[1,0,1]
	s_waitcnt lgkmcnt(4)
	v_pk_fma_f32 v[104:105], v[16:17], v[182:183], v[104:105] op_sel_hi:[1,0,1]
	s_waitcnt lgkmcnt(3)
	v_pk_fma_f32 v[156:157], v[16:17], v[184:185], v[156:157] op_sel_hi:[1,0,1]
	s_waitcnt lgkmcnt(2)
	v_pk_fma_f32 v[160:161], v[16:17], v[186:187], v[160:161] op_sel_hi:[1,0,1]
	s_waitcnt lgkmcnt(1)
	v_pk_fma_f32 v[164:165], v[16:17], v[188:189], v[164:165] op_sel_hi:[1,0,1]
	s_waitcnt lgkmcnt(0)
	v_pk_fma_f32 v[16:17], v[16:17], v[190:191], v[20:21] op_sel_hi:[1,0,1]
	v_mov_b32_e32 v20, v177
	v_pk_fma_f32 v[26:27], v[18:19], v[180:181], v[26:27] op_sel_hi:[1,0,1]
	v_pk_fma_f32 v[166:167], v[18:19], v[178:179], v[166:167] op_sel_hi:[1,0,1]
	v_pk_fma_f32 v[158:159], v[18:19], v[182:183], v[158:159] op_sel_hi:[1,0,1]
	v_pk_fma_f32 v[168:169], v[18:19], v[184:185], v[168:169] op_sel_hi:[1,0,1]
	v_pk_fma_f32 v[174:175], v[18:19], v[186:187], v[174:175] op_sel_hi:[1,0,1]
	v_pk_fma_f32 v[162:163], v[18:19], v[188:189], v[162:163] op_sel_hi:[1,0,1]
	v_pk_fma_f32 v[18:19], v[18:19], v[190:191], v[22:23] op_sel_hi:[1,0,1]
	s_waitcnt vmcnt(2)
	v_pk_fma_f32 v[22:23], v[10:11], v[20:21], v[4:5] op_sel_hi:[1,0,1]
	v_mov_b32_e32 v4, v181
	v_pk_fma_f32 v[176:177], v[8:9], v[20:21], v[6:7] op_sel_hi:[1,0,1]
	v_pk_fma_f32 v[26:27], v[10:11], v[4:5], v[26:27] op_sel_hi:[1,0,1]
	v_pk_fma_f32 v[24:25], v[8:9], v[4:5], v[24:25] op_sel_hi:[1,0,1]
	v_mov_b32_e32 v4, v179
	v_mov_b32_e32 v20, v185
	v_pk_fma_f32 v[166:167], v[10:11], v[4:5], v[166:167] op_sel_hi:[1,0,1]
	v_pk_fma_f32 v[102:103], v[8:9], v[4:5], v[102:103] op_sel_hi:[1,0,1]
	v_mov_b32_e32 v4, v183
	v_mov_b32_e32 v89, v29
	v_pk_fma_f32 v[168:169], v[10:11], v[20:21], v[168:169] op_sel_hi:[1,0,1]
	v_pk_fma_f32 v[156:157], v[8:9], v[20:21], v[156:157] op_sel_hi:[1,0,1]
	v_mov_b32_e32 v20, v187
	v_pk_fma_f32 v[158:159], v[10:11], v[4:5], v[158:159] op_sel_hi:[1,0,1]
	v_pk_fma_f32 v[104:105], v[8:9], v[4:5], v[104:105] op_sel_hi:[1,0,1]
	v_lshl_add_u64 v[4:5], v[100:101], 0, v[88:89]
	v_pk_fma_f32 v[174:175], v[10:11], v[20:21], v[174:175] op_sel_hi:[1,0,1]
	v_pk_fma_f32 v[160:161], v[8:9], v[20:21], v[160:161] op_sel_hi:[1,0,1]
	v_mov_b32_e32 v20, v189
	v_mov_b32_e32 v178, v191
	v_mov_b32_e32 v91, v29
	global_load_dwordx4 v[4:7], v[4:5], off
	v_pk_fma_f32 v[164:165], v[8:9], v[20:21], v[164:165] op_sel_hi:[1,0,1]
	v_pk_fma_f32 v[16:17], v[8:9], v[178:179], v[16:17] op_sel_hi:[1,0,1]
	v_lshl_add_u64 v[8:9], v[100:101], 0, v[90:91]
	v_pk_fma_f32 v[162:163], v[10:11], v[20:21], v[162:163] op_sel_hi:[1,0,1]
	v_pk_fma_f32 v[18:19], v[10:11], v[178:179], v[18:19] op_sel_hi:[1,0,1]
	global_load_dwordx4 v[8:11], v[8:9], off
	v_add_u32_e32 v21, 0xc00, v126
	ds_read2_b32 v[180:181], v21 offset1:32
	v_add_u32_e32 v20, 0x1c00, v126
	v_add_u32_e32 v75, 0x7c00, v126
	ds_read2_b32 v[182:183], v20 offset1:32
	ds_read2_b32 v[194:195], v75 offset1:32
	s_waitcnt vmcnt(3) lgkmcnt(2)
	v_pk_fma_f32 v[178:179], v[14:15], v[180:181], v[22:23] op_sel_hi:[1,0,1]
	v_add_u32_e32 v23, 0x2c00, v126
	ds_read2_b32 v[184:185], v23 offset1:32
	v_add_u32_e32 v22, 0x3c00, v126
	ds_read2_b32 v[186:187], v22 offset1:32
	v_add_u32_e32 v69, 0x4c00, v126
	ds_read2_b32 v[188:189], v69 offset1:32
	v_add_u32_e32 v71, 0x5c00, v126
	v_add_u32_e32 v73, 0x6c00, v126
	ds_read2_b32 v[190:191], v71 offset1:32
	ds_read2_b32 v[192:193], v73 offset1:32
	s_waitcnt lgkmcnt(6)
	v_pk_fma_f32 v[26:27], v[14:15], v[182:183], v[26:27] op_sel_hi:[1,0,1]
	v_pk_fma_f32 v[24:25], v[12:13], v[182:183], v[24:25] op_sel_hi:[1,0,1]
	s_waitcnt lgkmcnt(5)
	v_pk_fma_f32 v[196:197], v[12:13], v[194:195], v[16:17] op_sel_hi:[1,0,1]
	v_mov_b32_e32 v16, v183
	s_waitcnt lgkmcnt(4)
	v_pk_fma_f32 v[166:167], v[14:15], v[184:185], v[166:167] op_sel_hi:[1,0,1]
	v_pk_fma_f32 v[102:103], v[12:13], v[184:185], v[102:103] op_sel_hi:[1,0,1]
	s_waitcnt lgkmcnt(3)
	v_pk_fma_f32 v[158:159], v[14:15], v[186:187], v[158:159] op_sel_hi:[1,0,1]
	v_pk_fma_f32 v[104:105], v[12:13], v[186:187], v[104:105] op_sel_hi:[1,0,1]
	s_waitcnt lgkmcnt(2)
	v_pk_fma_f32 v[168:169], v[14:15], v[188:189], v[168:169] op_sel_hi:[1,0,1]
	v_pk_fma_f32 v[156:157], v[12:13], v[188:189], v[156:157] op_sel_hi:[1,0,1]
	v_pk_fma_f32 v[176:177], v[12:13], v[180:181], v[176:177] op_sel_hi:[1,0,1]
	s_waitcnt lgkmcnt(1)
	v_pk_fma_f32 v[174:175], v[14:15], v[190:191], v[174:175] op_sel_hi:[1,0,1]
	s_waitcnt vmcnt(2)
	v_pk_fma_f32 v[26:27], v[2:3], v[16:17], v[26:27] op_sel_hi:[1,0,1]
	v_pk_fma_f32 v[24:25], v[0:1], v[16:17], v[24:25] op_sel_hi:[1,0,1]
	v_mov_b32_e32 v16, v185
	v_pk_fma_f32 v[166:167], v[2:3], v[16:17], v[166:167] op_sel_hi:[1,0,1]
	v_pk_fma_f32 v[102:103], v[0:1], v[16:17], v[102:103] op_sel_hi:[1,0,1]
	v_mov_b32_e32 v16, v187
	v_pk_fma_f32 v[158:159], v[2:3], v[16:17], v[158:159] op_sel_hi:[1,0,1]
	v_pk_fma_f32 v[104:105], v[0:1], v[16:17], v[104:105] op_sel_hi:[1,0,1]
	v_mov_b32_e32 v16, v189
	v_pk_fma_f32 v[160:161], v[12:13], v[190:191], v[160:161] op_sel_hi:[1,0,1]
	s_waitcnt lgkmcnt(0)
; __device__ __forceinline__ void p0_mod_item(const Params& p, LAS unsigned char* lds, int item) {
;     ...
; #pragma unroll 32
;     for (int pass = 0; pass < 32; ++pass) { const int i = pass * 32 + rs; const f32x4 w = *(const f32x4*)(p.w_ada + (size_t)i * NMOD + j0 + 4 * l16);
; #pragma unroll
;         for (int b = 0; b < 8; ++b) acc[b] += cs[b * DM + i] * w; }
	v_pk_fma_f32 v[164:165], v[12:13], v[192:193], v[164:165] op_sel_hi:[1,0,1]
	v_mov_b32_e32 v12, v181
	v_mov_b32_e32 v93, v29
	v_pk_fma_f32 v[168:169], v[2:3], v[16:17], v[168:169] op_sel_hi:[1,0,1]
	v_pk_fma_f32 v[156:157], v[0:1], v[16:17], v[156:157] op_sel_hi:[1,0,1]
	v_mov_b32_e32 v16, v191
	v_pk_fma_f32 v[162:163], v[14:15], v[192:193], v[162:163] op_sel_hi:[1,0,1]
	v_pk_fma_f32 v[18:19], v[14:15], v[194:195], v[18:19] op_sel_hi:[1,0,1]
	v_pk_fma_f32 v[178:179], v[2:3], v[12:13], v[178:179] op_sel_hi:[1,0,1]
	v_pk_fma_f32 v[176:177], v[0:1], v[12:13], v[176:177] op_sel_hi:[1,0,1]
	v_lshl_add_u64 v[12:13], v[100:101], 0, v[92:93]
	v_pk_fma_f32 v[174:175], v[2:3], v[16:17], v[174:175] op_sel_hi:[1,0,1]
	v_pk_fma_f32 v[160:161], v[0:1], v[16:17], v[160:161] op_sel_hi:[1,0,1]
	v_mov_b32_e32 v16, v193
	v_mov_b32_e32 v180, v195
	global_load_dwordx4 v[12:15], v[12:13], off
	v_pk_fma_f32 v[162:163], v[2:3], v[16:17], v[162:163] op_sel_hi:[1,0,1]
	v_pk_fma_f32 v[182:183], v[2:3], v[180:181], v[18:19] op_sel_hi:[1,0,1]
	v_lshl_add_u64 v[2:3], v[100:101], 0, v[94:95]
	v_pk_fma_f32 v[164:165], v[0:1], v[16:17], v[164:165] op_sel_hi:[1,0,1]
	global_load_dwordx4 v[16:19], v[2:3], off
	ds_read2_b32 v[184:185], v21 offset0:64 offset1:96
	ds_read2_b32 v[186:187], v20 offset0:64 offset1:96
	v_pk_fma_f32 v[180:181], v[0:1], v[180:181], v[196:197] op_sel_hi:[1,0,1]
	ds_read2_b32 v[188:189], v23 offset0:64 offset1:96
	ds_read2_b32 v[190:191], v22 offset0:64 offset1:96
	ds_read2_b32 v[192:193], v69 offset0:64 offset1:96
	ds_read2_b32 v[194:195], v71 offset0:64 offset1:96
	ds_read2_b32 v[196:197], v73 offset0:64 offset1:96
	ds_read2_b32 v[198:199], v75 offset0:64 offset1:96
	v_lshl_add_u64 v[0:1], v[100:101], 0, v[96:97]
	global_load_dwordx4 v[0:3], v[0:1], off
	s_waitcnt vmcnt(4) lgkmcnt(7)
	v_pk_fma_f32 v[178:179], v[6:7], v[184:185], v[178:179] op_sel_hi:[1,0,1]
	v_pk_fma_f32 v[176:177], v[4:5], v[184:185], v[176:177] op_sel_hi:[1,0,1]
	s_waitcnt lgkmcnt(6)
	v_pk_fma_f32 v[24:25], v[4:5], v[186:187], v[24:25] op_sel_hi:[1,0,1]
	s_waitcnt lgkmcnt(5)
	v_pk_fma_f32 v[102:103], v[4:5], v[188:189], v[102:103] op_sel_hi:[1,0,1]
	s_waitcnt lgkmcnt(4)
	v_pk_fma_f32 v[104:105], v[4:5], v[190:191], v[104:105] op_sel_hi:[1,0,1]
	s_waitcnt lgkmcnt(3)
	v_pk_fma_f32 v[156:157], v[4:5], v[192:193], v[156:157] op_sel_hi:[1,0,1]
	s_waitcnt lgkmcnt(2)
	v_pk_fma_f32 v[160:161], v[4:5], v[194:195], v[160:161] op_sel_hi:[1,0,1]
	s_waitcnt lgkmcnt(1)
	v_pk_fma_f32 v[164:165], v[4:5], v[196:197], v[164:165] op_sel_hi:[1,0,1]
	s_waitcnt lgkmcnt(0)
	v_pk_fma_f32 v[180:181], v[4:5], v[198:199], v[180:181] op_sel_hi:[1,0,1]
	v_mov_b32_e32 v4, v185
	v_pk_fma_f32 v[26:27], v[6:7], v[186:187], v[26:27] op_sel_hi:[1,0,1]
	s_waitcnt vmcnt(3)
	v_pk_fma_f32 v[178:179], v[10:11], v[4:5], v[178:179] op_sel_hi:[1,0,1]
	v_pk_fma_f32 v[176:177], v[8:9], v[4:5], v[176:177] op_sel_hi:[1,0,1]
	v_mov_b32_e32 v4, v187
	v_pk_fma_f32 v[166:167], v[6:7], v[188:189], v[166:167] op_sel_hi:[1,0,1]
	v_pk_fma_f32 v[26:27], v[10:11], v[4:5], v[26:27] op_sel_hi:[1,0,1]
	v_pk_fma_f32 v[24:25], v[8:9], v[4:5], v[24:25] op_sel_hi:[1,0,1]
	v_mov_b32_e32 v4, v189
	v_pk_fma_f32 v[158:159], v[6:7], v[190:191], v[158:159] op_sel_hi:[1,0,1]
	v_pk_fma_f32 v[166:167], v[10:11], v[4:5], v[166:167] op_sel_hi:[1,0,1]
	v_pk_fma_f32 v[102:103], v[8:9], v[4:5], v[102:103] op_sel_hi:[1,0,1]
	v_mov_b32_e32 v4, v191
	v_pk_fma_f32 v[168:169], v[6:7], v[192:193], v[168:169] op_sel_hi:[1,0,1]
	v_pk_fma_f32 v[158:159], v[10:11], v[4:5], v[158:159] op_sel_hi:[1,0,1]
	v_pk_fma_f32 v[104:105], v[8:9], v[4:5], v[104:105] op_sel_hi:[1,0,1]
	v_mov_b32_e32 v4, v193
	v_pk_fma_f32 v[174:175], v[6:7], v[194:195], v[174:175] op_sel_hi:[1,0,1]
	v_pk_fma_f32 v[168:169], v[10:11], v[4:5], v[168:169] op_sel_hi:[1,0,1]
	v_pk_fma_f32 v[156:157], v[8:9], v[4:5], v[156:157] op_sel_hi:[1,0,1]
	v_mov_b32_e32 v4, v195
	v_pk_fma_f32 v[174:175], v[10:11], v[4:5], v[174:175] op_sel_hi:[1,0,1]
	v_pk_fma_f32 v[160:161], v[8:9], v[4:5], v[160:161] op_sel_hi:[1,0,1]
	v_lshl_add_u64 v[4:5], v[100:101], 0, v[98:99]
	v_pk_fma_f32 v[162:163], v[6:7], v[196:197], v[162:163] op_sel_hi:[1,0,1]
	v_pk_fma_f32 v[182:183], v[6:7], v[198:199], v[182:183] op_sel_hi:[1,0,1]
	global_load_dwordx4 v[4:7], v[4:5], off
	v_mov_b32_e32 v100, v197
	v_mov_b32_e32 v184, v199
	v_pk_fma_f32 v[162:163], v[10:11], v[100:101], v[162:163] op_sel_hi:[1,0,1]
	v_pk_fma_f32 v[100:101], v[8:9], v[100:101], v[164:165] op_sel_hi:[1,0,1]
	ds_read2_b32 v[164:165], v21 offset0:128 offset1:160
	v_pk_fma_f32 v[10:11], v[10:11], v[184:185], v[182:183] op_sel_hi:[1,0,1]
	ds_read2_b32 v[182:183], v20 offset0:128 offset1:160
	v_pk_fma_f32 v[8:9], v[8:9], v[184:185], v[180:181] op_sel_hi:[1,0,1]
	ds_read2_b32 v[180:181], v23 offset0:128 offset1:160
	ds_read2_b32 v[184:185], v22 offset0:128 offset1:160
	ds_read2_b32 v[186:187], v69 offset0:128 offset1:160
	ds_read2_b32 v[188:189], v71 offset0:128 offset1:160
	ds_read2_b32 v[190:191], v73 offset0:128 offset1:160
	ds_read2_b32 v[192:193], v75 offset0:128 offset1:160
	s_waitcnt vmcnt(3) lgkmcnt(7)
	v_pk_fma_f32 v[178:179], v[14:15], v[164:165], v[178:179] op_sel_hi:[1,0,1]
	v_pk_fma_f32 v[176:177], v[12:13], v[164:165], v[176:177] op_sel_hi:[1,0,1]
	s_waitcnt lgkmcnt(6)
	v_pk_fma_f32 v[26:27], v[14:15], v[182:183], v[26:27] op_sel_hi:[1,0,1]
	v_pk_fma_f32 v[24:25], v[12:13], v[182:183], v[24:25] op_sel_hi:[1,0,1]
	v_mov_b32_e32 v164, v183
	s_waitcnt lgkmcnt(5)
	v_pk_fma_f32 v[166:167], v[14:15], v[180:181], v[166:167] op_sel_hi:[1,0,1]
	v_pk_fma_f32 v[102:103], v[12:13], v[180:181], v[102:103] op_sel_hi:[1,0,1]
	s_waitcnt vmcnt(2)
; #define LAS __attribute__((address_space(3)))
; __device__ __forceinline__ void p0_mod_item(const Params& p, LAS unsigned char* lds, int item) {
;     ...
;     for (int pass = 0; pass < 32; ++pass) { const int i = pass * 32 + rs; const f32x4 w = *(const f32x4*)(p.w_ada + (size_t)i * NMOD + j0 + 4 * l16);
; #pragma unroll
;         for (int b = 0; b < 8; ++b) acc[b] += cs[b * DM + i] * w; }
; #pragma unroll
;     for (int b = 0; b < 8; ++b) *(LAS f32x4*)(red + (rs * 8 + b) * 64 + 4 * l16) = acc[b];
;     __syncthreads();
;     { const int b = tid >> 6, col = tid & 63; float s = p.b_ada[j0 + col];
	v_pk_fma_f32 v[26:27], v[18:19], v[164:165], v[26:27] op_sel_hi:[1,0,1]
	v_pk_fma_f32 v[24:25], v[16:17], v[164:165], v[24:25] op_sel_hi:[1,0,1]
	v_mov_b32_e32 v164, v181
	s_waitcnt lgkmcnt(4)
	v_pk_fma_f32 v[158:159], v[14:15], v[184:185], v[158:159] op_sel_hi:[1,0,1]
	v_pk_fma_f32 v[104:105], v[12:13], v[184:185], v[104:105] op_sel_hi:[1,0,1]
	v_pk_fma_f32 v[166:167], v[18:19], v[164:165], v[166:167] op_sel_hi:[1,0,1]
	v_pk_fma_f32 v[102:103], v[16:17], v[164:165], v[102:103] op_sel_hi:[1,0,1]
	v_mov_b32_e32 v164, v185
	s_waitcnt lgkmcnt(3)
	v_pk_fma_f32 v[168:169], v[14:15], v[186:187], v[168:169] op_sel_hi:[1,0,1]
	v_pk_fma_f32 v[156:157], v[12:13], v[186:187], v[156:157] op_sel_hi:[1,0,1]
	v_pk_fma_f32 v[158:159], v[18:19], v[164:165], v[158:159] op_sel_hi:[1,0,1]
	v_pk_fma_f32 v[104:105], v[16:17], v[164:165], v[104:105] op_sel_hi:[1,0,1]
	v_mov_b32_e32 v164, v187
	s_waitcnt lgkmcnt(2)
	v_pk_fma_f32 v[174:175], v[14:15], v[188:189], v[174:175] op_sel_hi:[1,0,1]
	v_pk_fma_f32 v[160:161], v[12:13], v[188:189], v[160:161] op_sel_hi:[1,0,1]
	s_waitcnt lgkmcnt(1)
	v_pk_fma_f32 v[100:101], v[12:13], v[190:191], v[100:101] op_sel_hi:[1,0,1]
	s_waitcnt lgkmcnt(0)
	v_pk_fma_f32 v[8:9], v[12:13], v[192:193], v[8:9] op_sel_hi:[1,0,1]
	v_mov_b32_e32 v12, v165
	v_pk_fma_f32 v[168:169], v[18:19], v[164:165], v[168:169] op_sel_hi:[1,0,1]
	v_pk_fma_f32 v[156:157], v[16:17], v[164:165], v[156:157] op_sel_hi:[1,0,1]
	v_mov_b32_e32 v164, v189
	v_pk_fma_f32 v[162:163], v[14:15], v[190:191], v[162:163] op_sel_hi:[1,0,1]
	v_pk_fma_f32 v[10:11], v[14:15], v[192:193], v[10:11] op_sel_hi:[1,0,1]
	v_pk_fma_f32 v[14:15], v[18:19], v[12:13], v[178:179] op_sel_hi:[1,0,1]
	v_pk_fma_f32 v[12:13], v[16:17], v[12:13], v[176:177] op_sel_hi:[1,0,1]
	v_pk_fma_f32 v[174:175], v[18:19], v[164:165], v[174:175] op_sel_hi:[1,0,1]
	v_pk_fma_f32 v[160:161], v[16:17], v[164:165], v[160:161] op_sel_hi:[1,0,1]
	v_mov_b32_e32 v164, v191
	v_mov_b32_e32 v176, v193
	v_pk_fma_f32 v[162:163], v[18:19], v[164:165], v[162:163] op_sel_hi:[1,0,1]
	v_pk_fma_f32 v[100:101], v[16:17], v[164:165], v[100:101] op_sel_hi:[1,0,1]
	v_pk_fma_f32 v[10:11], v[18:19], v[176:177], v[10:11] op_sel_hi:[1,0,1]
	ds_read2_b32 v[18:19], v20 offset0:192 offset1:224
	v_pk_fma_f32 v[8:9], v[16:17], v[176:177], v[8:9] op_sel_hi:[1,0,1]
	ds_read2_b32 v[16:17], v23 offset0:192 offset1:224
	ds_read2_b32 v[164:165], v21 offset0:192 offset1:224
	ds_read2_b32 v[22:23], v22 offset0:192 offset1:224
	s_waitcnt vmcnt(1) lgkmcnt(3)
	v_pk_fma_f32 v[20:21], v[2:3], v[18:19], v[26:27] op_sel_hi:[1,0,1]
	ds_read2_b32 v[176:177], v71 offset0:192 offset1:224
	s_waitcnt lgkmcnt(3)
	v_pk_fma_f32 v[26:27], v[2:3], v[16:17], v[166:167] op_sel_hi:[1,0,1]
	ds_read2_b32 v[166:167], v69 offset0:192 offset1:224
	ds_read2_b32 v[178:179], v73 offset0:192 offset1:224
	ds_read2_b32 v[180:181], v75 offset0:192 offset1:224
	s_waitcnt lgkmcnt(5)
	v_pk_fma_f32 v[14:15], v[2:3], v[164:165], v[14:15] op_sel_hi:[1,0,1]
	v_pk_fma_f32 v[12:13], v[0:1], v[164:165], v[12:13] op_sel_hi:[1,0,1]
	v_pk_fma_f32 v[24:25], v[0:1], v[18:19], v[24:25] op_sel_hi:[1,0,1]
	v_pk_fma_f32 v[102:103], v[0:1], v[16:17], v[102:103] op_sel_hi:[1,0,1]
	s_waitcnt lgkmcnt(4)
	v_pk_fma_f32 v[158:159], v[2:3], v[22:23], v[158:159] op_sel_hi:[1,0,1]
	v_pk_fma_f32 v[104:105], v[0:1], v[22:23], v[104:105] op_sel_hi:[1,0,1]
	s_waitcnt lgkmcnt(2)
	v_pk_fma_f32 v[156:157], v[0:1], v[166:167], v[156:157] op_sel_hi:[1,0,1]
	v_pk_fma_f32 v[160:161], v[0:1], v[176:177], v[160:161] op_sel_hi:[1,0,1]
	s_waitcnt lgkmcnt(1)
	v_pk_fma_f32 v[100:101], v[0:1], v[178:179], v[100:101] op_sel_hi:[1,0,1]
	s_waitcnt lgkmcnt(0)
	v_pk_fma_f32 v[184:185], v[0:1], v[180:181], v[8:9] op_sel_hi:[1,0,1]
	v_mov_b32_e32 v0, v165
	v_mov_b32_e32 v16, v23
	v_pk_fma_f32 v[168:169], v[2:3], v[166:167], v[168:169] op_sel_hi:[1,0,1]
	v_pk_fma_f32 v[174:175], v[2:3], v[176:177], v[174:175] op_sel_hi:[1,0,1]
	v_pk_fma_f32 v[162:163], v[2:3], v[178:179], v[162:163] op_sel_hi:[1,0,1]
	v_pk_fma_f32 v[182:183], v[2:3], v[180:181], v[10:11] op_sel_hi:[1,0,1]
	s_waitcnt vmcnt(0)
	v_pk_fma_f32 v[2:3], v[6:7], v[0:1], v[14:15] op_sel_hi:[1,0,1]
	v_pk_fma_f32 v[0:1], v[4:5], v[0:1], v[12:13] op_sel_hi:[1,0,1]
	v_mov_b32_e32 v8, v19
	v_mov_b32_e32 v12, v17
	v_pk_fma_f32 v[18:19], v[6:7], v[16:17], v[158:159] op_sel_hi:[1,0,1]
	v_pk_fma_f32 v[16:17], v[4:5], v[16:17], v[104:105] op_sel_hi:[1,0,1]
	v_mov_b32_e32 v104, v179
	v_pk_fma_f32 v[10:11], v[6:7], v[8:9], v[20:21] op_sel_hi:[1,0,1]
	v_pk_fma_f32 v[8:9], v[4:5], v[8:9], v[24:25] op_sel_hi:[1,0,1]
	v_pk_fma_f32 v[14:15], v[6:7], v[12:13], v[26:27] op_sel_hi:[1,0,1]
	v_pk_fma_f32 v[12:13], v[4:5], v[12:13], v[102:103] op_sel_hi:[1,0,1]
	v_mov_b32_e32 v20, v167
	v_mov_b32_e32 v24, v177
	v_pk_fma_f32 v[102:103], v[6:7], v[104:105], v[162:163] op_sel_hi:[1,0,1]
	v_pk_fma_f32 v[100:101], v[4:5], v[104:105], v[100:101] op_sel_hi:[1,0,1]
	v_mov_b32_e32 v104, v181
	v_add_u32_e32 v69, v121, v122
	v_pk_fma_f32 v[22:23], v[6:7], v[20:21], v[168:169] op_sel_hi:[1,0,1]
	v_pk_fma_f32 v[20:21], v[4:5], v[20:21], v[156:157] op_sel_hi:[1,0,1]
	v_pk_fma_f32 v[26:27], v[6:7], v[24:25], v[174:175] op_sel_hi:[1,0,1]
	v_pk_fma_f32 v[24:25], v[4:5], v[24:25], v[160:161] op_sel_hi:[1,0,1]
	v_pk_fma_f32 v[6:7], v[6:7], v[104:105], v[182:183] op_sel_hi:[1,0,1]
	v_pk_fma_f32 v[4:5], v[4:5], v[104:105], v[184:185] op_sel_hi:[1,0,1]
	ds_write_b128 v69, v[0:3] offset:32768
	ds_write_b128 v69, v[8:11] offset:33024
	ds_write_b128 v69, v[12:15] offset:33280
	ds_write_b128 v69, v[16:19] offset:33536
	ds_write_b128 v69, v[20:23] offset:33792
	ds_write_b128 v69, v[24:27] offset:34048
	ds_write_b128 v69, v[100:103] offset:34304
	ds_write_b128 v69, v[4:7] offset:34560
	v_or_b32_e32 v0, s14, v37
	v_ashrrev_i32_e32 v1, 31, v0
	v_lshl_add_u64 v[0:1], v[0:1], 2, s[42:43]
	s_waitcnt lgkmcnt(0)
	s_barrier
	global_load_dword v0, v[0:1], off
